# GEMM epilogue cross-row reductions (P2/P3/P5): ds_bpermute + lgkmcnt round trips replaced by v_permlane16/32_swap sums
# baseline (speedup 1.0000x reference)
.LBB0_263:
	v_mbcnt_lo_u32_b32 v242, -1, 0
	v_mbcnt_hi_u32_b32 v242, -1, v242
	v_bfe_u32 v242, v242, 4, 1
	v_mul_u32_u24_e32 v242, 24, v242
	v_mov_b32_e32 v243, 0
	v_lshl_or_b32 v140, s77, 8, v180
	v_lshl_add_u32 v184, s76, 8, v176
	v_ashrrev_i32_e32 v141, 31, v140
	v_lshlrev_b64 v[186:187], 1, v[140:141]
	v_ashrrev_i32_e32 v185, 31, v184
	v_lshl_add_u64 v[142:143], s[34:35], 0, v[186:187]
	v_lshlrev_b64 v[144:145], 12, v[184:185]
	v_lshl_add_u64 v[146:147], v[142:143], 0, v[144:145]
	v_lshl_add_u64 v[252:253], v[146:147], 0, v[242:243]
	global_load_dwordx4 v[208:211], v[252:253], off
	v_lshl_add_u64 v[252:253], v[146:147], 0, v[242:243]
	global_load_dwordx4 v[212:215], v[252:253], off offset:256
	v_or_b32_e32 v146, 16, v184
	v_or_b32_e32 v148, 32, v184
	v_or_b32_e32 v150, 48, v184
	v_ashrrev_i32_e32 v147, 31, v146
	v_ashrrev_i32_e32 v149, 31, v148
	v_ashrrev_i32_e32 v151, 31, v150
	v_lshlrev_b64 v[166:167], 12, v[146:147]
	v_lshlrev_b64 v[156:157], 12, v[148:149]
	v_lshlrev_b64 v[146:147], 12, v[150:151]
	v_lshl_add_u64 v[148:149], v[142:143], 0, v[166:167]
	v_lshl_add_u64 v[150:151], v[142:143], 0, v[156:157]
	v_lshl_add_u64 v[196:197], v[142:143], 0, v[146:147]
	v_lshl_add_u64 v[252:253], v[148:149], 0, v[242:243]
	global_load_dwordx4 v[216:219], v[252:253], off
	v_lshl_add_u64 v[252:253], v[148:149], 0, v[242:243]
	global_load_dwordx4 v[220:223], v[252:253], off offset:256
	v_lshl_add_u64 v[252:253], v[150:151], 0, v[242:243]
	global_load_dwordx4 v[224:227], v[252:253], off
	v_lshl_add_u64 v[252:253], v[150:151], 0, v[242:243]
	global_load_dwordx4 v[228:231], v[252:253], off offset:256
	v_lshl_add_u64 v[252:253], v[196:197], 0, v[242:243]
	global_load_dwordx4 v[244:247], v[252:253], off
	s_nop 0
	v_lshl_add_u64 v[252:253], v[196:197], 0, v[242:243]
	global_load_dwordx4 v[248:251], v[252:253], off offset:256
	v_lshl_add_u64 v[196:197], s[34:35], 0, v[144:145]
	v_lshl_add_u64 v[186:187], v[196:197], 0, v[186:187]
	s_waitcnt vmcnt(0)
	v_permlane16_swap_b32 v208, v210
	v_permlane16_swap_b32 v209, v211
	v_lshlrev_b32_e32 v196, 16, v208
	v_and_b32_e32 v197, 0xffff0000, v208
	v_lshlrev_b32_e32 v188, 16, v209
	v_and_b32_e32 v189, 0xffff0000, v209
	v_lshlrev_b32_e32 v198, 16, v210
	v_and_b32_e32 v199, 0xffff0000, v210
	v_lshlrev_b32_e32 v190, 16, v211
	v_and_b32_e32 v191, 0xffff0000, v211
	v_permlane16_swap_b32 v212, v214
	v_permlane16_swap_b32 v213, v215
	v_lshlrev_b32_e32 v200, 16, v212
	v_and_b32_e32 v201, 0xffff0000, v212
	v_lshlrev_b32_e32 v192, 16, v213
	v_and_b32_e32 v193, 0xffff0000, v213
	v_lshlrev_b32_e32 v202, 16, v214
	v_and_b32_e32 v203, 0xffff0000, v214
	v_lshlrev_b32_e32 v194, 16, v215
	v_and_b32_e32 v195, 0xffff0000, v215
	v_pk_fma_f32 v[126:127], v[126:127], 0.5, v[188:189] op_sel_hi:[1,0,1]
	v_pk_fma_f32 v[124:125], v[124:125], 0.5, v[196:197] op_sel_hi:[1,0,1]
	v_pk_fma_f32 v[122:123], v[122:123], 0.5, v[190:191] op_sel_hi:[1,0,1]
	v_pk_fma_f32 v[120:121], v[120:121], 0.5, v[198:199] op_sel_hi:[1,0,1]
	v_pk_fma_f32 v[118:119], v[118:119], 0.5, v[192:193] op_sel_hi:[1,0,1]
	v_pk_fma_f32 v[116:117], v[116:117], 0.5, v[200:201] op_sel_hi:[1,0,1]
	v_pk_fma_f32 v[188:189], v[114:115], 0.5, v[194:195] op_sel_hi:[1,0,1]
	v_mul_f32_e32 v190, v125, v125
	v_mul_f32_e32 v191, v127, v127
	v_cvt_pk_bf16_f32 v232, v124, v125
	v_cvt_pk_bf16_f32 v233, v126, v127
	v_mul_f32_e32 v125, v121, v121
	v_mul_f32_e32 v127, v123, v123
	v_pk_fma_f32 v[112:113], v[112:113], 0.5, v[202:203] op_sel_hi:[1,0,1]
	v_mul_f32_e32 v192, v117, v117
	v_mul_f32_e32 v193, v119, v119
	v_fmac_f32_e32 v190, v124, v124
	v_fmac_f32_e32 v191, v126, v126
	v_fmac_f32_e32 v125, v120, v120
	v_fmac_f32_e32 v127, v122, v122
	v_mul_f32_e32 v194, v113, v113
	v_mul_f32_e32 v195, v189, v189
	v_cvt_pk_bf16_f32 v234, v120, v121
	v_fmac_f32_e32 v192, v116, v116
	v_fmac_f32_e32 v193, v118, v118
	v_add_f32_e32 v120, v190, v191
	v_add_f32_e32 v121, v125, v127
	v_cvt_pk_bf16_f32 v235, v122, v123
	v_fmac_f32_e32 v194, v112, v112
	v_fmac_f32_e32 v195, v188, v188
	v_add_f32_e32 v122, v192, v193
	v_add_f32_e32 v120, v120, v121
	v_add_f32_e32 v120, v120, v122
	v_add_f32_e32 v121, v194, v195
	v_add_f32_e32 v120, v120, v121
	v_mov_b32_e32 v121, v120
	v_mov_b32_e32 v254, v120
	s_nop 1
	v_permlane16_swap_b32 v121, v254
	s_nop 1
	v_permlane16_swap_b32 v232, v234
	v_permlane16_swap_b32 v233, v235
	v_lshl_add_u64 v[240:241], v[186:187], 0, v[242:243]
	global_store_dwordx4 v[240:241], v[232:235], off
	v_cvt_pk_bf16_f32 v236, v116, v117
	v_cvt_pk_bf16_f32 v237, v118, v119
	s_waitcnt lgkmcnt(0)
	v_add_f32_e32 v114, v254, v121
	v_mov_b32_e32 v115, v114
	v_mov_b32_e32 v254, v114
	s_nop 1
	v_permlane32_swap_b32 v115, v254
	v_cvt_pk_bf16_f32 v238, v112, v113
	v_cvt_pk_bf16_f32 v239, v188, v189
	s_nop 1
	v_permlane16_swap_b32 v236, v238
	v_permlane16_swap_b32 v237, v239
	v_lshl_add_u64 v[240:241], v[186:187], 0, v[242:243]
	global_store_dwordx4 v[240:241], v[236:239], off offset:256
	v_lshl_add_u64 v[112:113], v[184:185], 2, s[26:27]
	s_and_saveexec_b64 s[50:51], s[6:7]
	s_cbranch_execz .LBB0_265
	s_waitcnt lgkmcnt(0)
	v_add_f32_e32 v114, v254, v115
	global_atomic_add_f32 v[112:113], v114, off
.LBB0_265:
	s_or_b64 exec, exec, s[50:51]
	v_permlane16_swap_b32 v216, v218
	v_permlane16_swap_b32 v217, v219
	v_lshlrev_b32_e32 v114, 16, v216
	s_waitcnt lgkmcnt(0)
	v_and_b32_e32 v115, 0xffff0000, v216
	v_lshlrev_b32_e32 v116, 16, v217
	v_and_b32_e32 v117, 0xffff0000, v217
	v_pk_fma_f32 v[110:111], v[110:111], 0.5, v[116:117] op_sel_hi:[1,0,1]
	v_pk_fma_f32 v[108:109], v[108:109], 0.5, v[114:115] op_sel_hi:[1,0,1]
	v_mul_f32_e32 v115, v111, v111
	v_mul_f32_e32 v114, v109, v109
	v_lshlrev_b32_e32 v118, 16, v218
	v_and_b32_e32 v119, 0xffff0000, v218
	v_lshlrev_b32_e32 v120, 16, v219
	v_and_b32_e32 v121, 0xffff0000, v219
	v_fmac_f32_e32 v114, v108, v108
	v_fmac_f32_e32 v115, v110, v110
	v_cvt_pk_bf16_f32 v232, v108, v109
	v_cvt_pk_bf16_f32 v233, v110, v111
	v_lshl_add_u64 v[110:111], s[34:35], 0, v[166:167]
	v_lshl_add_u64 v[110:111], v[140:141], 1, v[110:111]
	v_pk_fma_f32 v[106:107], v[106:107], 0.5, v[120:121] op_sel_hi:[1,0,1]
	v_pk_fma_f32 v[104:105], v[104:105], 0.5, v[118:119] op_sel_hi:[1,0,1]
	v_permlane16_swap_b32 v220, v222
	v_permlane16_swap_b32 v221, v223
	v_lshlrev_b32_e32 v122, 16, v220
	v_and_b32_e32 v123, 0xffff0000, v220
	v_lshlrev_b32_e32 v124, 16, v221
	v_and_b32_e32 v125, 0xffff0000, v221
	v_mul_f32_e32 v108, v105, v105
	v_mul_f32_e32 v109, v107, v107
	v_fmac_f32_e32 v108, v104, v104
	v_fmac_f32_e32 v109, v106, v106
	v_pk_fma_f32 v[102:103], v[102:103], 0.5, v[124:125] op_sel_hi:[1,0,1]
	v_pk_fma_f32 v[100:101], v[100:101], 0.5, v[122:123] op_sel_hi:[1,0,1]
	v_add_f32_e32 v108, v108, v109
	v_cvt_pk_bf16_f32 v234, v104, v105
	v_mul_f32_e32 v105, v101, v101
	v_mul_f32_e32 v109, v103, v103
	v_add_f32_e32 v114, v114, v115
	v_fmac_f32_e32 v105, v100, v100
	v_fmac_f32_e32 v109, v102, v102
	v_lshlrev_b32_e32 v126, 16, v222
	v_and_b32_e32 v127, 0xffff0000, v222
	v_lshlrev_b32_e32 v168, 16, v223
	v_and_b32_e32 v169, 0xffff0000, v223
	v_add_f32_e32 v108, v114, v108
	v_add_f32_e32 v105, v105, v109
	v_add_f32_e32 v105, v108, v105
	v_pk_fma_f32 v[98:99], v[98:99], 0.5, v[168:169] op_sel_hi:[1,0,1]
	v_pk_fma_f32 v[108:109], v[96:97], 0.5, v[126:127] op_sel_hi:[1,0,1]
	v_mul_f32_e32 v97, v99, v99
	v_mul_f32_e32 v96, v109, v109
	v_fmac_f32_e32 v96, v108, v108
	v_fmac_f32_e32 v97, v98, v98
	v_add_f32_e32 v96, v96, v97
	v_add_f32_e32 v96, v105, v96
	v_mov_b32_e32 v97, v96
	v_mov_b32_e32 v254, v96
	s_nop 1
	v_permlane16_swap_b32 v97, v254
	v_cvt_pk_bf16_f32 v235, v106, v107
	s_nop 1
	v_permlane16_swap_b32 v232, v234
	v_permlane16_swap_b32 v233, v235
	v_lshl_add_u64 v[240:241], v[110:111], 0, v[242:243]
	global_store_dwordx4 v[240:241], v[232:235], off
	v_cvt_pk_bf16_f32 v236, v100, v101
	v_cvt_pk_bf16_f32 v237, v102, v103
	s_waitcnt lgkmcnt(0)
	v_add_f32_e32 v96, v254, v97
	v_mov_b32_e32 v97, v96
	v_mov_b32_e32 v254, v96
	s_nop 1
	v_permlane32_swap_b32 v97, v254
	v_cvt_pk_bf16_f32 v238, v108, v109
	v_cvt_pk_bf16_f32 v239, v98, v99
	s_nop 1
	v_permlane16_swap_b32 v236, v238
	v_permlane16_swap_b32 v237, v239
	v_lshl_add_u64 v[240:241], v[110:111], 0, v[242:243]
	global_store_dwordx4 v[240:241], v[236:239], off offset:256
	s_and_saveexec_b64 s[50:51], s[6:7]
	s_cbranch_execz .LBB0_267
	s_waitcnt lgkmcnt(0)
	v_add_f32_e32 v96, v254, v97
	global_atomic_add_f32 v[112:113], v96, off offset:64
.LBB0_267:
	s_or_b64 exec, exec, s[50:51]
	v_permlane16_swap_b32 v224, v226
	v_permlane16_swap_b32 v225, v227
	v_lshlrev_b32_e32 v96, 16, v224
	s_waitcnt lgkmcnt(0)
	v_and_b32_e32 v97, 0xffff0000, v224
	v_lshlrev_b32_e32 v98, 16, v225
	v_and_b32_e32 v99, 0xffff0000, v225
	v_pk_fma_f32 v[94:95], v[94:95], 0.5, v[98:99] op_sel_hi:[1,0,1]
	v_pk_fma_f32 v[92:93], v[92:93], 0.5, v[96:97] op_sel_hi:[1,0,1]
	v_mul_f32_e32 v97, v95, v95
	v_mul_f32_e32 v96, v93, v93
	v_lshlrev_b32_e32 v100, 16, v226
	v_and_b32_e32 v101, 0xffff0000, v226
	v_lshlrev_b32_e32 v102, 16, v227
	v_and_b32_e32 v103, 0xffff0000, v227
	v_fmac_f32_e32 v96, v92, v92
	v_fmac_f32_e32 v97, v94, v94
	v_cvt_pk_bf16_f32 v232, v92, v93
	v_cvt_pk_bf16_f32 v233, v94, v95
	v_lshl_add_u64 v[94:95], s[34:35], 0, v[156:157]
	v_lshl_add_u64 v[94:95], v[140:141], 1, v[94:95]
	v_pk_fma_f32 v[90:91], v[90:91], 0.5, v[102:103] op_sel_hi:[1,0,1]
	v_pk_fma_f32 v[88:89], v[88:89], 0.5, v[100:101] op_sel_hi:[1,0,1]
	v_permlane16_swap_b32 v228, v230
	v_permlane16_swap_b32 v229, v231
	v_lshlrev_b32_e32 v104, 16, v228
	v_and_b32_e32 v105, 0xffff0000, v228
	v_lshlrev_b32_e32 v106, 16, v229
	v_and_b32_e32 v107, 0xffff0000, v229
	v_mul_f32_e32 v92, v89, v89
	v_mul_f32_e32 v93, v91, v91
	v_fmac_f32_e32 v92, v88, v88
	v_fmac_f32_e32 v93, v90, v90
	v_pk_fma_f32 v[86:87], v[86:87], 0.5, v[106:107] op_sel_hi:[1,0,1]
	v_pk_fma_f32 v[84:85], v[84:85], 0.5, v[104:105] op_sel_hi:[1,0,1]
	v_add_f32_e32 v92, v92, v93
	v_cvt_pk_bf16_f32 v234, v88, v89
	v_mul_f32_e32 v89, v85, v85
	v_mul_f32_e32 v93, v87, v87
	v_add_f32_e32 v96, v96, v97
	v_fmac_f32_e32 v89, v84, v84
	v_fmac_f32_e32 v93, v86, v86
	v_lshlrev_b32_e32 v108, 16, v230
	v_and_b32_e32 v109, 0xffff0000, v230
	v_lshlrev_b32_e32 v110, 16, v231
	v_and_b32_e32 v111, 0xffff0000, v231
	v_add_f32_e32 v92, v96, v92
	v_add_f32_e32 v89, v89, v93
	v_add_f32_e32 v89, v92, v89
	v_pk_fma_f32 v[82:83], v[82:83], 0.5, v[110:111] op_sel_hi:[1,0,1]
	v_pk_fma_f32 v[92:93], v[80:81], 0.5, v[108:109] op_sel_hi:[1,0,1]
	v_mul_f32_e32 v81, v83, v83
	v_mul_f32_e32 v80, v93, v93
	v_fmac_f32_e32 v80, v92, v92
	v_fmac_f32_e32 v81, v82, v82
	v_add_f32_e32 v80, v80, v81
	v_add_f32_e32 v80, v89, v80
	v_mov_b32_e32 v81, v80
	v_mov_b32_e32 v254, v80
	s_nop 1
	v_permlane16_swap_b32 v81, v254
	v_cvt_pk_bf16_f32 v235, v90, v91
	s_nop 1
	v_permlane16_swap_b32 v232, v234
	v_permlane16_swap_b32 v233, v235
	v_lshl_add_u64 v[240:241], v[94:95], 0, v[242:243]
	global_store_dwordx4 v[240:241], v[232:235], off
	v_cvt_pk_bf16_f32 v236, v84, v85
	v_cvt_pk_bf16_f32 v237, v86, v87
	s_waitcnt lgkmcnt(0)
	v_add_f32_e32 v80, v254, v81
	v_mov_b32_e32 v81, v80
	v_mov_b32_e32 v254, v80
	s_nop 1
	v_permlane32_swap_b32 v81, v254
	v_cvt_pk_bf16_f32 v238, v92, v93
	v_cvt_pk_bf16_f32 v239, v82, v83
	s_nop 1
	v_permlane16_swap_b32 v236, v238
	v_permlane16_swap_b32 v237, v239
	v_lshl_add_u64 v[240:241], v[94:95], 0, v[242:243]
	global_store_dwordx4 v[240:241], v[236:239], off offset:256
	s_and_saveexec_b64 s[50:51], s[6:7]
	s_cbranch_execz .LBB0_269
	s_waitcnt lgkmcnt(0)
	v_add_f32_e32 v80, v254, v81
	global_atomic_add_f32 v[112:113], v80, off offset:128
.LBB0_269:
	s_or_b64 exec, exec, s[50:51]
	v_permlane16_swap_b32 v244, v246
	v_permlane16_swap_b32 v245, v247
	v_lshlrev_b32_e32 v80, 16, v244
	s_waitcnt lgkmcnt(0)
	v_and_b32_e32 v81, 0xffff0000, v244
	v_lshlrev_b32_e32 v82, 16, v245
	v_and_b32_e32 v83, 0xffff0000, v245
	v_pk_fma_f32 v[78:79], v[78:79], 0.5, v[82:83] op_sel_hi:[1,0,1]
	v_pk_fma_f32 v[76:77], v[76:77], 0.5, v[80:81] op_sel_hi:[1,0,1]
	v_mul_f32_e32 v81, v79, v79
	v_mul_f32_e32 v80, v77, v77
	v_lshlrev_b32_e32 v84, 16, v246
	v_and_b32_e32 v85, 0xffff0000, v246
	v_lshlrev_b32_e32 v86, 16, v247
	v_and_b32_e32 v87, 0xffff0000, v247
	v_fmac_f32_e32 v80, v76, v76
	v_fmac_f32_e32 v81, v78, v78
	v_cvt_pk_bf16_f32 v232, v76, v77
	v_cvt_pk_bf16_f32 v233, v78, v79
	v_lshl_add_u64 v[78:79], s[34:35], 0, v[146:147]
	v_lshl_add_u64 v[78:79], v[140:141], 1, v[78:79]
	v_pk_fma_f32 v[74:75], v[74:75], 0.5, v[86:87] op_sel_hi:[1,0,1]
	v_pk_fma_f32 v[72:73], v[72:73], 0.5, v[84:85] op_sel_hi:[1,0,1]
	v_permlane16_swap_b32 v248, v250
	v_permlane16_swap_b32 v249, v251
	v_lshlrev_b32_e32 v88, 16, v248
	v_and_b32_e32 v89, 0xffff0000, v248
	v_lshlrev_b32_e32 v90, 16, v249
	v_and_b32_e32 v91, 0xffff0000, v249
	v_mul_f32_e32 v76, v73, v73
	v_mul_f32_e32 v77, v75, v75
	v_fmac_f32_e32 v76, v72, v72
	v_fmac_f32_e32 v77, v74, v74
	v_pk_fma_f32 v[70:71], v[70:71], 0.5, v[90:91] op_sel_hi:[1,0,1]
	v_pk_fma_f32 v[68:69], v[68:69], 0.5, v[88:89] op_sel_hi:[1,0,1]
	v_add_f32_e32 v76, v76, v77
	v_cvt_pk_bf16_f32 v234, v72, v73
	v_mul_f32_e32 v73, v69, v69
	v_mul_f32_e32 v77, v71, v71
	v_add_f32_e32 v80, v80, v81
	v_fmac_f32_e32 v73, v68, v68
	v_fmac_f32_e32 v77, v70, v70
	v_lshlrev_b32_e32 v92, 16, v250
	v_and_b32_e32 v93, 0xffff0000, v250
	v_lshlrev_b32_e32 v94, 16, v251
	v_and_b32_e32 v95, 0xffff0000, v251
	v_add_f32_e32 v76, v80, v76
	v_add_f32_e32 v73, v73, v77
	v_add_f32_e32 v73, v76, v73
	v_pk_fma_f32 v[66:67], v[66:67], 0.5, v[94:95] op_sel_hi:[1,0,1]
	v_pk_fma_f32 v[76:77], v[64:65], 0.5, v[92:93] op_sel_hi:[1,0,1]
	v_mul_f32_e32 v65, v67, v67
	v_mul_f32_e32 v64, v77, v77
	v_fmac_f32_e32 v64, v76, v76
	v_fmac_f32_e32 v65, v66, v66
	v_add_f32_e32 v64, v64, v65
	v_add_f32_e32 v64, v73, v64
	v_mov_b32_e32 v65, v64
	v_mov_b32_e32 v254, v64
	s_nop 1
	v_permlane16_swap_b32 v65, v254
	v_cvt_pk_bf16_f32 v235, v74, v75
	s_nop 1
	v_permlane16_swap_b32 v232, v234
	v_permlane16_swap_b32 v233, v235
	v_lshl_add_u64 v[240:241], v[78:79], 0, v[242:243]
	global_store_dwordx4 v[240:241], v[232:235], off
	v_cvt_pk_bf16_f32 v236, v68, v69
	v_cvt_pk_bf16_f32 v237, v70, v71
	s_waitcnt lgkmcnt(0)
	v_add_f32_e32 v64, v254, v65
	v_mov_b32_e32 v65, v64
	v_mov_b32_e32 v254, v64
	s_nop 1
	v_permlane32_swap_b32 v65, v254
	v_cvt_pk_bf16_f32 v238, v76, v77
	v_cvt_pk_bf16_f32 v239, v66, v67
	s_nop 1
	v_permlane16_swap_b32 v236, v238
	v_permlane16_swap_b32 v237, v239
	v_lshl_add_u64 v[240:241], v[78:79], 0, v[242:243]
	global_store_dwordx4 v[240:241], v[236:239], off offset:256
	s_and_saveexec_b64 s[50:51], s[6:7]
	s_cbranch_execz .LBB0_271
	s_waitcnt lgkmcnt(0)
	v_add_f32_e32 v64, v254, v65
	global_atomic_add_f32 v[112:113], v64, off offset:192
.LBB0_271:
	s_or_b64 exec, exec, s[50:51]
	s_mov_b64 s[50:51], 0x80000
	v_lshl_add_u64 v[94:95], v[144:145], 0, s[50:51]
	s_waitcnt lgkmcnt(0)
	v_lshl_add_u64 v[64:65], v[142:143], 0, v[94:95]
	v_lshl_add_u64 v[252:253], v[64:65], 0, v[242:243]
	global_load_dwordx4 v[208:211], v[252:253], off
	v_lshl_add_u64 v[252:253], v[64:65], 0, v[242:243]
	global_load_dwordx4 v[212:215], v[252:253], off offset:256
	s_mov_b64 s[50:51], 0x90000
	v_lshl_add_u64 v[74:75], v[144:145], 0, s[20:21]
	v_lshl_add_u64 v[64:65], v[144:145], 0, s[46:47]
	v_lshl_add_u64 v[84:85], v[144:145], 0, s[50:51]
	v_lshl_add_u64 v[66:67], v[142:143], 0, v[74:75]
	v_lshl_add_u64 v[86:87], v[142:143], 0, v[64:65]
	v_lshl_add_u64 v[104:105], v[142:143], 0, v[84:85]
	v_lshl_add_u64 v[252:253], v[66:67], 0, v[242:243]
	global_load_dwordx4 v[216:219], v[252:253], off
	v_lshl_add_u64 v[252:253], v[66:67], 0, v[242:243]
	global_load_dwordx4 v[220:223], v[252:253], off offset:256
	v_lshl_add_u64 v[252:253], v[86:87], 0, v[242:243]
	global_load_dwordx4 v[224:227], v[252:253], off
	v_lshl_add_u64 v[252:253], v[86:87], 0, v[242:243]
	global_load_dwordx4 v[228:231], v[252:253], off offset:256
	s_nop 0
	v_lshl_add_u64 v[252:253], v[104:105], 0, v[242:243]
	global_load_dwordx4 v[244:247], v[252:253], off
	v_lshl_add_u64 v[252:253], v[104:105], 0, v[242:243]
	global_load_dwordx4 v[248:251], v[252:253], off offset:256
	s_nop 0
	v_lshl_add_u64 v[94:95], s[34:35], 0, v[94:95]
	v_lshl_add_u64 v[94:95], v[140:141], 1, v[94:95]
	s_waitcnt vmcnt(7)
	v_permlane16_swap_b32 v208, v210
	v_permlane16_swap_b32 v209, v211
	v_lshlrev_b32_e32 v104, 16, v208
	v_and_b32_e32 v105, 0xffff0000, v208
	v_lshlrev_b32_e32 v96, 16, v209
	v_and_b32_e32 v97, 0xffff0000, v209
	s_waitcnt vmcnt(7)
	v_lshlrev_b32_e32 v106, 16, v210
	v_and_b32_e32 v107, 0xffff0000, v210
	v_lshlrev_b32_e32 v98, 16, v211
	v_and_b32_e32 v99, 0xffff0000, v211
	s_waitcnt vmcnt(6)
	v_permlane16_swap_b32 v212, v214
	v_permlane16_swap_b32 v213, v215
	v_lshlrev_b32_e32 v108, 16, v212
	v_and_b32_e32 v109, 0xffff0000, v212
	v_lshlrev_b32_e32 v100, 16, v213
	v_and_b32_e32 v101, 0xffff0000, v213
	s_waitcnt vmcnt(6)
	v_lshlrev_b32_e32 v110, 16, v214
	v_and_b32_e32 v111, 0xffff0000, v214
	v_pk_fma_f32 v[62:63], v[62:63], 0.5, v[96:97] op_sel_hi:[1,0,1]
	v_pk_fma_f32 v[60:61], v[60:61], 0.5, v[104:105] op_sel_hi:[1,0,1]
	v_pk_fma_f32 v[58:59], v[58:59], 0.5, v[98:99] op_sel_hi:[1,0,1]
	v_pk_fma_f32 v[56:57], v[56:57], 0.5, v[106:107] op_sel_hi:[1,0,1]
	v_lshlrev_b32_e32 v102, 16, v215
	v_and_b32_e32 v103, 0xffff0000, v215
	v_pk_fma_f32 v[54:55], v[54:55], 0.5, v[100:101] op_sel_hi:[1,0,1]
	v_pk_fma_f32 v[52:53], v[52:53], 0.5, v[108:109] op_sel_hi:[1,0,1]
	v_pk_fma_f32 v[96:97], v[48:49], 0.5, v[110:111] op_sel_hi:[1,0,1]
	v_mul_f32_e32 v98, v61, v61
	v_mul_f32_e32 v99, v63, v63
	v_cvt_pk_bf16_f32 v232, v60, v61
	v_cvt_pk_bf16_f32 v233, v62, v63
	v_mul_f32_e32 v61, v57, v57
	v_mul_f32_e32 v63, v59, v59
	v_pk_fma_f32 v[50:51], v[50:51], 0.5, v[102:103] op_sel_hi:[1,0,1]
	v_mul_f32_e32 v100, v53, v53
	v_mul_f32_e32 v101, v55, v55
	v_fmac_f32_e32 v98, v60, v60
	v_fmac_f32_e32 v99, v62, v62
	v_fmac_f32_e32 v61, v56, v56
	v_fmac_f32_e32 v63, v58, v58
	v_mul_f32_e32 v102, v97, v97
	v_mul_f32_e32 v103, v51, v51
	v_cvt_pk_bf16_f32 v234, v56, v57
	v_fmac_f32_e32 v100, v52, v52
	v_fmac_f32_e32 v101, v54, v54
	v_add_f32_e32 v49, v98, v99
	v_add_f32_e32 v56, v61, v63
	v_fmac_f32_e32 v102, v96, v96
	v_fmac_f32_e32 v103, v50, v50
	v_add_f32_e32 v57, v100, v101
	v_add_f32_e32 v49, v49, v56
	v_add_f32_e32 v49, v49, v57
	v_add_f32_e32 v56, v102, v103
	v_add_f32_e32 v56, v49, v56
	v_mov_b32_e32 v57, v56
	v_mov_b32_e32 v254, v56
	s_nop 1
	v_permlane16_swap_b32 v57, v254
	v_cvt_pk_bf16_f32 v235, v58, v59
	s_nop 1
	v_permlane16_swap_b32 v232, v234
	v_permlane16_swap_b32 v233, v235
	v_lshl_add_u64 v[240:241], v[94:95], 0, v[242:243]
	global_store_dwordx4 v[240:241], v[232:235], off
	v_cvt_pk_bf16_f32 v236, v52, v53
	v_cvt_pk_bf16_f32 v237, v54, v55
	s_waitcnt lgkmcnt(0)
	v_add_f32_e32 v48, v254, v57
	v_mov_b32_e32 v49, v48
	v_mov_b32_e32 v254, v48
	s_nop 1
	v_permlane32_swap_b32 v49, v254
	v_cvt_pk_bf16_f32 v238, v96, v97
	v_cvt_pk_bf16_f32 v239, v50, v51
	s_nop 1
	v_permlane16_swap_b32 v236, v238
	v_permlane16_swap_b32 v237, v239
	v_lshl_add_u64 v[240:241], v[94:95], 0, v[242:243]
	global_store_dwordx4 v[240:241], v[236:239], off offset:256
	s_and_saveexec_b64 s[50:51], s[6:7]
	s_cbranch_execz .LBB0_273
	s_waitcnt lgkmcnt(0)
	v_add_f32_e32 v48, v254, v49
	global_atomic_add_f32 v[112:113], v48, off offset:512
.LBB0_273:
	s_or_b64 exec, exec, s[50:51]
	s_waitcnt vmcnt(3)
	v_permlane16_swap_b32 v244, v246
	v_permlane16_swap_b32 v245, v247
	v_lshlrev_b32_e32 v48, 16, v244
	s_waitcnt lgkmcnt(0)
	v_and_b32_e32 v49, 0xffff0000, v244
	v_lshlrev_b32_e32 v50, 16, v245
	v_and_b32_e32 v51, 0xffff0000, v245
	v_pk_fma_f32 v[46:47], v[46:47], 0.5, v[50:51] op_sel_hi:[1,0,1]
	v_pk_fma_f32 v[44:45], v[44:45], 0.5, v[48:49] op_sel_hi:[1,0,1]
	v_mul_f32_e32 v49, v47, v47
	v_mul_f32_e32 v48, v45, v45
	s_waitcnt vmcnt(3)
	v_lshlrev_b32_e32 v52, 16, v246
	v_and_b32_e32 v53, 0xffff0000, v246
	v_lshlrev_b32_e32 v54, 16, v247
	v_and_b32_e32 v55, 0xffff0000, v247
	v_fmac_f32_e32 v48, v44, v44
	v_fmac_f32_e32 v49, v46, v46
	v_cvt_pk_bf16_f32 v232, v44, v45
	v_cvt_pk_bf16_f32 v233, v46, v47
	v_lshl_add_u64 v[46:47], s[34:35], 0, v[84:85]
	v_lshl_add_u64 v[46:47], v[140:141], 1, v[46:47]
	v_pk_fma_f32 v[42:43], v[42:43], 0.5, v[54:55] op_sel_hi:[1,0,1]
	v_pk_fma_f32 v[40:41], v[40:41], 0.5, v[52:53] op_sel_hi:[1,0,1]
	s_waitcnt vmcnt(2)
	v_permlane16_swap_b32 v248, v250
	v_permlane16_swap_b32 v249, v251
	v_lshlrev_b32_e32 v56, 16, v248
	v_and_b32_e32 v57, 0xffff0000, v248
	v_lshlrev_b32_e32 v58, 16, v249
	v_and_b32_e32 v59, 0xffff0000, v249
	v_mul_f32_e32 v44, v41, v41
	v_mul_f32_e32 v45, v43, v43
	v_fmac_f32_e32 v44, v40, v40
	v_fmac_f32_e32 v45, v42, v42
	v_pk_fma_f32 v[38:39], v[38:39], 0.5, v[58:59] op_sel_hi:[1,0,1]
	v_pk_fma_f32 v[36:37], v[36:37], 0.5, v[56:57] op_sel_hi:[1,0,1]
	v_add_f32_e32 v44, v44, v45
	v_cvt_pk_bf16_f32 v234, v40, v41
	v_mul_f32_e32 v41, v37, v37
	v_mul_f32_e32 v45, v39, v39
	v_add_f32_e32 v48, v48, v49
	v_fmac_f32_e32 v41, v36, v36
	v_fmac_f32_e32 v45, v38, v38
	s_waitcnt vmcnt(2)
	v_lshlrev_b32_e32 v60, 16, v250
	v_and_b32_e32 v61, 0xffff0000, v250
	v_lshlrev_b32_e32 v62, 16, v251
	v_and_b32_e32 v63, 0xffff0000, v251
	v_add_f32_e32 v44, v48, v44
	v_add_f32_e32 v41, v41, v45
	v_add_f32_e32 v41, v44, v41
	v_pk_fma_f32 v[34:35], v[34:35], 0.5, v[62:63] op_sel_hi:[1,0,1]
	v_pk_fma_f32 v[44:45], v[32:33], 0.5, v[60:61] op_sel_hi:[1,0,1]
	v_mul_f32_e32 v33, v35, v35
	v_mul_f32_e32 v32, v45, v45
	v_fmac_f32_e32 v32, v44, v44
	v_fmac_f32_e32 v33, v34, v34
	v_add_f32_e32 v32, v32, v33
	v_add_f32_e32 v32, v41, v32
	v_mov_b32_e32 v33, v32
	v_mov_b32_e32 v254, v32
	s_nop 1
	v_permlane16_swap_b32 v33, v254
	v_cvt_pk_bf16_f32 v235, v42, v43
	s_nop 1
	v_permlane16_swap_b32 v232, v234
	v_permlane16_swap_b32 v233, v235
	v_lshl_add_u64 v[240:241], v[46:47], 0, v[242:243]
	global_store_dwordx4 v[240:241], v[232:235], off
	v_cvt_pk_bf16_f32 v236, v36, v37
	v_cvt_pk_bf16_f32 v237, v38, v39
	s_waitcnt lgkmcnt(0)
	v_add_f32_e32 v32, v254, v33
	v_mov_b32_e32 v33, v32
	v_mov_b32_e32 v254, v32
	s_nop 1
	v_permlane32_swap_b32 v33, v254
	v_cvt_pk_bf16_f32 v238, v44, v45
	v_cvt_pk_bf16_f32 v239, v34, v35
	s_nop 1
	v_permlane16_swap_b32 v236, v238
	v_permlane16_swap_b32 v237, v239
	v_lshl_add_u64 v[240:241], v[46:47], 0, v[242:243]
	global_store_dwordx4 v[240:241], v[236:239], off offset:256
	s_and_saveexec_b64 s[50:51], s[6:7]
	s_cbranch_execz .LBB0_275
	s_waitcnt lgkmcnt(0)
	v_add_f32_e32 v32, v254, v33
	global_atomic_add_f32 v[112:113], v32, off offset:576
.LBB0_275:
	s_or_b64 exec, exec, s[50:51]
	v_permlane16_swap_b32 v216, v218
	v_permlane16_swap_b32 v217, v219
	v_lshlrev_b32_e32 v32, 16, v216
	s_waitcnt lgkmcnt(0)
	v_and_b32_e32 v33, 0xffff0000, v216
	v_lshlrev_b32_e32 v34, 16, v217
	v_and_b32_e32 v35, 0xffff0000, v217
	v_pk_fma_f32 v[30:31], v[30:31], 0.5, v[34:35] op_sel_hi:[1,0,1]
	v_pk_fma_f32 v[28:29], v[28:29], 0.5, v[32:33] op_sel_hi:[1,0,1]
	v_mul_f32_e32 v33, v31, v31
	v_mul_f32_e32 v32, v29, v29
	v_lshlrev_b32_e32 v36, 16, v218
	v_and_b32_e32 v37, 0xffff0000, v218
	v_lshlrev_b32_e32 v38, 16, v219
	v_and_b32_e32 v39, 0xffff0000, v219
	v_fmac_f32_e32 v32, v28, v28
	v_fmac_f32_e32 v33, v30, v30
	v_cvt_pk_bf16_f32 v232, v28, v29
	v_cvt_pk_bf16_f32 v233, v30, v31
	v_lshl_add_u64 v[30:31], s[34:35], 0, v[74:75]
	v_lshl_add_u64 v[30:31], v[140:141], 1, v[30:31]
	v_pk_fma_f32 v[26:27], v[26:27], 0.5, v[38:39] op_sel_hi:[1,0,1]
	v_pk_fma_f32 v[24:25], v[24:25], 0.5, v[36:37] op_sel_hi:[1,0,1]
	v_permlane16_swap_b32 v220, v222
	v_permlane16_swap_b32 v221, v223
	v_lshlrev_b32_e32 v40, 16, v220
	v_and_b32_e32 v41, 0xffff0000, v220
	v_lshlrev_b32_e32 v42, 16, v221
	v_and_b32_e32 v43, 0xffff0000, v221
	v_mul_f32_e32 v28, v25, v25
	v_mul_f32_e32 v29, v27, v27
	v_fmac_f32_e32 v28, v24, v24
	v_fmac_f32_e32 v29, v26, v26
	v_pk_fma_f32 v[22:23], v[22:23], 0.5, v[42:43] op_sel_hi:[1,0,1]
	v_pk_fma_f32 v[20:21], v[20:21], 0.5, v[40:41] op_sel_hi:[1,0,1]
	v_add_f32_e32 v28, v28, v29
	v_cvt_pk_bf16_f32 v234, v24, v25
	v_mul_f32_e32 v25, v21, v21
	v_mul_f32_e32 v29, v23, v23
	v_add_f32_e32 v32, v32, v33
	v_fmac_f32_e32 v25, v20, v20
	v_fmac_f32_e32 v29, v22, v22
	v_lshlrev_b32_e32 v44, 16, v222
	v_and_b32_e32 v45, 0xffff0000, v222
	v_lshlrev_b32_e32 v46, 16, v223
	v_and_b32_e32 v47, 0xffff0000, v223
	v_add_f32_e32 v28, v32, v28
	v_add_f32_e32 v25, v25, v29
	v_add_f32_e32 v25, v28, v25
	v_pk_fma_f32 v[18:19], v[18:19], 0.5, v[46:47] op_sel_hi:[1,0,1]
	v_pk_fma_f32 v[28:29], v[16:17], 0.5, v[44:45] op_sel_hi:[1,0,1]
	v_mul_f32_e32 v17, v19, v19
	v_mul_f32_e32 v16, v29, v29
	v_fmac_f32_e32 v16, v28, v28
	v_fmac_f32_e32 v17, v18, v18
	v_add_f32_e32 v16, v16, v17
	v_add_f32_e32 v16, v25, v16
	v_mov_b32_e32 v17, v16
	v_mov_b32_e32 v254, v16
	s_nop 1
	v_permlane16_swap_b32 v17, v254
	v_cvt_pk_bf16_f32 v235, v26, v27
	s_nop 1
	v_permlane16_swap_b32 v232, v234
	v_permlane16_swap_b32 v233, v235
	v_lshl_add_u64 v[240:241], v[30:31], 0, v[242:243]
	global_store_dwordx4 v[240:241], v[232:235], off
	v_cvt_pk_bf16_f32 v236, v20, v21
	v_cvt_pk_bf16_f32 v237, v22, v23
	s_waitcnt lgkmcnt(0)
	v_add_f32_e32 v16, v254, v17
	v_mov_b32_e32 v17, v16
	v_mov_b32_e32 v254, v16
	s_nop 1
	v_permlane32_swap_b32 v17, v254
	v_cvt_pk_bf16_f32 v238, v28, v29
	v_cvt_pk_bf16_f32 v239, v18, v19
	s_nop 1
	v_permlane16_swap_b32 v236, v238
	v_permlane16_swap_b32 v237, v239
	v_lshl_add_u64 v[240:241], v[30:31], 0, v[242:243]
	global_store_dwordx4 v[240:241], v[236:239], off offset:256
	s_and_saveexec_b64 s[50:51], s[6:7]
	s_cbranch_execz .LBB0_277
	s_waitcnt lgkmcnt(0)
	v_add_f32_e32 v16, v254, v17
	global_atomic_add_f32 v[112:113], v16, off offset:640
.LBB0_277:
	s_or_b64 exec, exec, s[50:51]
	v_permlane16_swap_b32 v224, v226
	v_permlane16_swap_b32 v225, v227
	v_lshlrev_b32_e32 v16, 16, v224
	s_waitcnt lgkmcnt(0)
	v_and_b32_e32 v17, 0xffff0000, v224
	v_lshlrev_b32_e32 v18, 16, v225
	v_and_b32_e32 v19, 0xffff0000, v225
	v_pk_fma_f32 v[14:15], v[14:15], 0.5, v[18:19] op_sel_hi:[1,0,1]
	v_pk_fma_f32 v[12:13], v[12:13], 0.5, v[16:17] op_sel_hi:[1,0,1]
	v_mul_f32_e32 v17, v15, v15
	v_mul_f32_e32 v16, v13, v13
	v_lshlrev_b32_e32 v20, 16, v226
	v_and_b32_e32 v21, 0xffff0000, v226
	v_lshlrev_b32_e32 v22, 16, v227
	v_and_b32_e32 v23, 0xffff0000, v227
	v_fmac_f32_e32 v16, v12, v12
	v_fmac_f32_e32 v17, v14, v14
	v_cvt_pk_bf16_f32 v232, v12, v13
	v_cvt_pk_bf16_f32 v233, v14, v15
	v_lshl_add_u64 v[14:15], s[34:35], 0, v[64:65]
	v_lshl_add_u64 v[14:15], v[140:141], 1, v[14:15]
	v_pk_fma_f32 v[10:11], v[10:11], 0.5, v[22:23] op_sel_hi:[1,0,1]
	v_pk_fma_f32 v[8:9], v[8:9], 0.5, v[20:21] op_sel_hi:[1,0,1]
	v_permlane16_swap_b32 v228, v230
	v_permlane16_swap_b32 v229, v231
	v_lshlrev_b32_e32 v24, 16, v228
	v_and_b32_e32 v25, 0xffff0000, v228
	v_lshlrev_b32_e32 v26, 16, v229
	v_and_b32_e32 v27, 0xffff0000, v229
	v_mul_f32_e32 v12, v9, v9
	v_mul_f32_e32 v13, v11, v11
	v_fmac_f32_e32 v12, v8, v8
	v_fmac_f32_e32 v13, v10, v10
	v_pk_fma_f32 v[6:7], v[6:7], 0.5, v[26:27] op_sel_hi:[1,0,1]
	v_pk_fma_f32 v[4:5], v[4:5], 0.5, v[24:25] op_sel_hi:[1,0,1]
	v_add_f32_e32 v12, v12, v13
	v_cvt_pk_bf16_f32 v234, v8, v9
	v_mul_f32_e32 v9, v5, v5
	v_mul_f32_e32 v13, v7, v7
	v_add_f32_e32 v16, v16, v17
	v_fmac_f32_e32 v9, v4, v4
	v_fmac_f32_e32 v13, v6, v6
	v_lshlrev_b32_e32 v28, 16, v230
	v_and_b32_e32 v29, 0xffff0000, v230
	v_lshlrev_b32_e32 v30, 16, v231
	v_and_b32_e32 v31, 0xffff0000, v231
	v_add_f32_e32 v12, v16, v12
	v_add_f32_e32 v9, v9, v13
	v_add_f32_e32 v9, v12, v9
	v_pk_fma_f32 v[2:3], v[2:3], 0.5, v[30:31] op_sel_hi:[1,0,1]
	v_pk_fma_f32 v[12:13], v[0:1], 0.5, v[28:29] op_sel_hi:[1,0,1]
	v_mul_f32_e32 v1, v3, v3
	v_mul_f32_e32 v0, v13, v13
	v_fmac_f32_e32 v0, v12, v12
	v_fmac_f32_e32 v1, v2, v2
	v_add_f32_e32 v0, v0, v1
	v_add_f32_e32 v0, v9, v0
	v_mov_b32_e32 v1, v0
	v_mov_b32_e32 v254, v0
	s_nop 1
	v_permlane16_swap_b32 v1, v254
	v_cvt_pk_bf16_f32 v235, v10, v11
	s_nop 1
	v_permlane16_swap_b32 v232, v234
	v_permlane16_swap_b32 v233, v235
	v_lshl_add_u64 v[240:241], v[14:15], 0, v[242:243]
	global_store_dwordx4 v[240:241], v[232:235], off
	v_cvt_pk_bf16_f32 v236, v4, v5
	v_cvt_pk_bf16_f32 v237, v6, v7
	s_waitcnt lgkmcnt(0)
	v_add_f32_e32 v0, v254, v1
	v_mov_b32_e32 v1, v0
	v_mov_b32_e32 v254, v0
	s_nop 1
	v_permlane32_swap_b32 v1, v254
	v_cvt_pk_bf16_f32 v238, v12, v13
	v_cvt_pk_bf16_f32 v239, v2, v3
	s_nop 1
	v_permlane16_swap_b32 v236, v238
	v_permlane16_swap_b32 v237, v239
	v_lshl_add_u64 v[240:241], v[14:15], 0, v[242:243]
	global_store_dwordx4 v[240:241], v[236:239], off offset:256
	s_and_saveexec_b64 s[50:51], s[6:7]
	s_cbranch_execz .LBB0_279
	s_waitcnt lgkmcnt(0)
	v_add_f32_e32 v0, v254, v1
	global_atomic_add_f32 v[112:113], v0, off offset:704

.LBB0_355:
	s_waitcnt vmcnt(0)
	v_fmamk_f32 v134, v134, 0x3a000000, v246
	v_rsq_f32_e32 v134, v134
	v_ashrrev_i32_e32 v159, 4, v148
	s_andn2_b64 vcc, exec, s[14:15]
	v_pk_mul_f32 v[226:227], v[110:111], v[134:135] op_sel_hi:[1,0]
	v_fmamk_f32 v110, v133, 0x3a000000, v246
	v_rsq_f32_e32 v110, v110
	v_pk_mul_f32 v[230:231], v[104:105], v[134:135] op_sel_hi:[1,0]
	v_pk_mul_f32 v[238:239], v[120:121], v[134:135] op_sel_hi:[1,0]
	v_pk_mul_f32 v[236:237], v[126:127], v[134:135] op_sel_hi:[1,0]
	v_pk_mul_f32 v[208:209], v[94:95], v[110:111] op_sel_hi:[1,0]
	v_fmamk_f32 v94, v132, 0x3a000000, v246
	v_rsq_f32_e32 v104, v94
	v_pk_mul_f32 v[212:213], v[88:89], v[110:111] op_sel_hi:[1,0]
	v_pk_mul_f32 v[220:221], v[112:113], v[110:111] op_sel_hi:[1,0]
	v_pk_mul_f32 v[240:241], v[124:125], v[134:135] op_sel_hi:[1,0]
	v_pk_mul_f32 v[88:89], v[78:79], v[104:105] op_sel_hi:[1,0]
	v_fmamk_f32 v78, v131, 0x3a000000, v246
	v_rsq_f32_e32 v78, v78
	v_pk_mul_f32 v[234:235], v[122:123], v[134:135] op_sel_hi:[1,0]
	v_pk_mul_f32 v[232:233], v[108:109], v[134:135] op_sel_hi:[1,0]
	v_pk_mul_f32 v[228:229], v[106:107], v[134:135] op_sel_hi:[1,0]
	v_pk_mul_f32 v[112:113], v[70:71], v[78:79] op_sel_hi:[1,0]
	v_fmamk_f32 v70, v129, 0x3a000000, v246
	v_rsq_f32_e32 v70, v70
	v_pk_mul_f32 v[218:219], v[118:119], v[110:111] op_sel_hi:[1,0]
	v_pk_mul_f32 v[222:223], v[116:117], v[110:111] op_sel_hi:[1,0]
	v_pk_mul_f32 v[216:217], v[114:115], v[110:111] op_sel_hi:[1,0]
	v_pk_mul_f32 v[120:121], v[46:47], v[70:71] op_sel_hi:[1,0]
	v_fmamk_f32 v46, v128, 0x3a000000, v246
	v_rsq_f32_e32 v46, v46
	v_pk_mul_f32 v[214:215], v[92:93], v[110:111] op_sel_hi:[1,0]
	v_pk_mul_f32 v[210:211], v[90:91], v[110:111] op_sel_hi:[1,0]
	v_pk_mul_f32 v[202:203], v[102:103], v[104:105] op_sel_hi:[1,0]
	v_pk_mul_f32 v[128:129], v[30:31], v[46:47] op_sel_hi:[1,0]
	v_fmamk_f32 v30, v130, 0x3a000000, v246
	v_rsq_f32_e32 v30, v30
	v_pk_mul_f32 v[206:207], v[100:101], v[104:105] op_sel_hi:[1,0]
	v_pk_mul_f32 v[200:201], v[98:99], v[104:105] op_sel_hi:[1,0]
	v_pk_mul_f32 v[204:205], v[96:97], v[104:105] op_sel_hi:[1,0]
	v_pk_mul_f32 v[136:137], v[14:15], v[30:31] op_sel_hi:[1,0]
	v_fmamk_f32 v14, v138, 0x3a000000, v246
	v_rsq_f32_e32 v14, v14
	v_pk_mul_f32 v[94:95], v[76:77], v[104:105] op_sel_hi:[1,0]
	v_pk_mul_f32 v[92:93], v[74:75], v[104:105] op_sel_hi:[1,0]
	v_pk_mul_f32 v[90:91], v[72:73], v[104:105] op_sel_hi:[1,0]
	v_pk_mul_f32 v[96:97], v[86:87], v[78:79] op_sel_hi:[1,0]
	v_pk_mul_f32 v[102:103], v[84:85], v[78:79] op_sel_hi:[1,0]
	v_pk_mul_f32 v[100:101], v[82:83], v[78:79] op_sel_hi:[1,0]
	v_pk_mul_f32 v[98:99], v[80:81], v[78:79] op_sel_hi:[1,0]
	v_pk_mul_f32 v[118:119], v[68:69], v[78:79] op_sel_hi:[1,0]
	v_pk_mul_f32 v[116:117], v[66:67], v[78:79] op_sel_hi:[1,0]
	v_pk_mul_f32 v[114:115], v[64:65], v[78:79] op_sel_hi:[1,0]
	v_pk_mul_f32 v[194:195], v[62:63], v[70:71] op_sel_hi:[1,0]
	v_pk_mul_f32 v[198:199], v[60:61], v[70:71] op_sel_hi:[1,0]
	v_pk_mul_f32 v[192:193], v[58:59], v[70:71] op_sel_hi:[1,0]
	v_pk_mul_f32 v[196:197], v[56:57], v[70:71] op_sel_hi:[1,0]
	v_pk_mul_f32 v[126:127], v[44:45], v[70:71] op_sel_hi:[1,0]
	v_pk_mul_f32 v[124:125], v[42:43], v[70:71] op_sel_hi:[1,0]
	v_pk_mul_f32 v[122:123], v[40:41], v[70:71] op_sel_hi:[1,0]
	v_pk_mul_f32 v[186:187], v[54:55], v[46:47] op_sel_hi:[1,0]
	v_pk_mul_f32 v[190:191], v[52:53], v[46:47] op_sel_hi:[1,0]
	v_pk_mul_f32 v[184:185], v[50:51], v[46:47] op_sel_hi:[1,0]
	v_pk_mul_f32 v[188:189], v[48:49], v[46:47] op_sel_hi:[1,0]
	v_pk_mul_f32 v[134:135], v[28:29], v[46:47] op_sel_hi:[1,0]
	v_pk_mul_f32 v[132:133], v[26:27], v[46:47] op_sel_hi:[1,0]
	v_pk_mul_f32 v[130:131], v[24:25], v[46:47] op_sel_hi:[1,0]
	v_pk_mul_f32 v[178:179], v[38:39], v[30:31] op_sel_hi:[1,0]
	v_pk_mul_f32 v[182:183], v[36:37], v[30:31] op_sel_hi:[1,0]
	v_pk_mul_f32 v[176:177], v[34:35], v[30:31] op_sel_hi:[1,0]
	v_pk_mul_f32 v[180:181], v[32:33], v[30:31] op_sel_hi:[1,0]
	v_pk_mul_f32 v[142:143], v[12:13], v[30:31] op_sel_hi:[1,0]
	v_pk_mul_f32 v[140:141], v[10:11], v[30:31] op_sel_hi:[1,0]
	v_pk_mul_f32 v[138:139], v[8:9], v[30:31] op_sel_hi:[1,0]
	v_pk_mul_f32 v[162:163], v[22:23], v[14:15] op_sel_hi:[1,0]
	v_pk_mul_f32 v[166:167], v[20:21], v[14:15] op_sel_hi:[1,0]
	v_pk_mul_f32 v[160:161], v[18:19], v[14:15] op_sel_hi:[1,0]
	v_pk_mul_f32 v[164:165], v[16:17], v[14:15] op_sel_hi:[1,0]
	v_pk_mul_f32 v[170:171], v[6:7], v[14:15] op_sel_hi:[1,0]
	v_pk_mul_f32 v[172:173], v[4:5], v[14:15] op_sel_hi:[1,0]
	v_pk_mul_f32 v[168:169], v[2:3], v[14:15] op_sel_hi:[1,0]
	v_pk_mul_f32 v[174:175], v[0:1], v[14:15] op_sel_hi:[1,0]
	s_cbranch_vccnz .LBB0_521
	v_mul_f32_e32 v2, v241, v241
	v_mul_f32_e32 v3, v237, v237
	v_fmac_f32_e32 v2, v240, v240
	v_fmac_f32_e32 v3, v236, v236
	v_add_f32_e32 v2, v2, v3
	v_mul_f32_e32 v3, v239, v239
	v_mul_f32_e32 v4, v235, v235
	v_fmac_f32_e32 v3, v238, v238
	v_fmac_f32_e32 v4, v234, v234
	v_lshlrev_b32_e32 v1, 2, v148
	v_add_f32_e32 v3, v3, v4
	v_xor_b32_e32 v0, 64, v1
	v_add_f32_e32 v2, v2, v3
	v_mov_b32_e32 v3, v2
	v_mov_b32_e32 v253, v2
	s_nop 1
	v_permlane16_swap_b32 v3, v253
	v_xor_b32_e32 v249, 0x80, v1
	v_add_lshl_u32 v1, v148, s94, 5
	v_cmp_gt_u32_e32 vcc, 16, v148
	s_waitcnt lgkmcnt(0)
	v_add_f32_e32 v3, v253, v3
	v_mov_b32_e32 v4, v3
	v_mov_b32_e32 v253, v3
	s_nop 1
	v_permlane32_swap_b32 v4, v253
	v_add_u32_e32 v2, s84, v1
	s_and_saveexec_b64 s[14:15], vcc
	s_cbranch_execz .LBB0_358
	s_waitcnt lgkmcnt(0)
	v_add_f32_e32 v3, v253, v4
	ds_write_b32 v2, v3
.LBB0_358:
	s_or_b64 exec, exec, s[14:15]
	v_mul_f32_e32 v3, v233, v233
	s_waitcnt lgkmcnt(0)
	v_mul_f32_e32 v4, v227, v227
	v_fmac_f32_e32 v3, v232, v232
	v_fmac_f32_e32 v4, v226, v226
	v_add_f32_e32 v3, v3, v4
	v_mul_f32_e32 v4, v231, v231
	v_mul_f32_e32 v5, v229, v229
	v_fmac_f32_e32 v4, v230, v230
	v_fmac_f32_e32 v5, v228, v228
	v_add_f32_e32 v4, v4, v5
	v_add_f32_e32 v3, v3, v4
	v_mov_b32_e32 v4, v3
	v_mov_b32_e32 v253, v3
	s_nop 1
	v_permlane16_swap_b32 v4, v253
	s_waitcnt lgkmcnt(0)
	v_add_f32_e32 v3, v253, v4
	v_mov_b32_e32 v4, v3
	v_mov_b32_e32 v253, v3
	s_nop 1
	v_permlane32_swap_b32 v4, v253
	s_and_saveexec_b64 s[14:15], vcc
	s_cbranch_execz .LBB0_360
	s_waitcnt lgkmcnt(0)
	v_add_f32_e32 v3, v253, v4
	ds_write_b32 v2, v3 offset:16
.LBB0_360:
	s_or_b64 exec, exec, s[14:15]
	v_mul_f32_e32 v2, v223, v223
	v_mul_f32_e32 v3, v219, v219
	v_fmac_f32_e32 v2, v222, v222
	v_fmac_f32_e32 v3, v218, v218
	v_add_f32_e32 v2, v2, v3
	v_mul_f32_e32 v3, v221, v221
	s_waitcnt lgkmcnt(0)
	v_mul_f32_e32 v4, v217, v217
	v_fmac_f32_e32 v3, v220, v220
	v_fmac_f32_e32 v4, v216, v216
	v_add_f32_e32 v3, v3, v4
	v_add_f32_e32 v2, v2, v3
	v_mov_b32_e32 v3, v2
	v_mov_b32_e32 v253, v2
	s_nop 1
	v_permlane16_swap_b32 v3, v253
	s_waitcnt lgkmcnt(0)
	v_add_f32_e32 v3, v253, v3
	v_mov_b32_e32 v4, v3
	v_mov_b32_e32 v253, v3
	s_nop 1
	v_permlane32_swap_b32 v4, v253
	v_add_u32_e32 v2, s85, v1
	s_and_saveexec_b64 s[14:15], vcc
	s_cbranch_execz .LBB0_362
	s_waitcnt lgkmcnt(0)
	v_add_f32_e32 v3, v253, v4
	ds_write_b32 v2, v3
.LBB0_362:
	s_or_b64 exec, exec, s[14:15]
	v_mul_f32_e32 v3, v215, v215
	s_waitcnt lgkmcnt(0)
	v_mul_f32_e32 v4, v209, v209
	v_fmac_f32_e32 v3, v214, v214
	v_fmac_f32_e32 v4, v208, v208
	v_add_f32_e32 v3, v3, v4
	v_mul_f32_e32 v4, v213, v213
	v_mul_f32_e32 v5, v211, v211
	v_fmac_f32_e32 v4, v212, v212
	v_fmac_f32_e32 v5, v210, v210
	v_add_f32_e32 v4, v4, v5
	v_add_f32_e32 v3, v3, v4
	v_mov_b32_e32 v4, v3
	v_mov_b32_e32 v253, v3
	s_nop 1
	v_permlane16_swap_b32 v4, v253
	s_waitcnt lgkmcnt(0)
	v_add_f32_e32 v3, v253, v4
	v_mov_b32_e32 v4, v3
	v_mov_b32_e32 v253, v3
	s_nop 1
	v_permlane32_swap_b32 v4, v253
	s_and_saveexec_b64 s[14:15], vcc
	s_cbranch_execz .LBB0_364
	s_waitcnt lgkmcnt(0)
	v_add_f32_e32 v3, v253, v4
	ds_write_b32 v2, v3 offset:16
.LBB0_364:
	s_or_b64 exec, exec, s[14:15]
	v_mul_f32_e32 v2, v207, v207
	v_mul_f32_e32 v3, v203, v203
	v_fmac_f32_e32 v2, v206, v206
	v_fmac_f32_e32 v3, v202, v202
	v_add_f32_e32 v2, v2, v3
	v_mul_f32_e32 v3, v205, v205
	s_waitcnt lgkmcnt(0)
	v_mul_f32_e32 v4, v201, v201
	v_fmac_f32_e32 v3, v204, v204
	v_fmac_f32_e32 v4, v200, v200
	v_add_f32_e32 v3, v3, v4
	v_add_f32_e32 v2, v2, v3
	v_mov_b32_e32 v3, v2
	v_mov_b32_e32 v253, v2
	s_nop 1
	v_permlane16_swap_b32 v3, v253
	s_waitcnt lgkmcnt(0)
	v_add_f32_e32 v3, v253, v3
	v_mov_b32_e32 v4, v3
	v_mov_b32_e32 v253, v3
	s_nop 1
	v_permlane32_swap_b32 v4, v253
	v_add_u32_e32 v2, s86, v1
	s_and_saveexec_b64 s[14:15], vcc
	s_cbranch_execz .LBB0_366
	s_waitcnt lgkmcnt(0)
	v_add_f32_e32 v3, v253, v4
	ds_write_b32 v2, v3
.LBB0_366:
	s_or_b64 exec, exec, s[14:15]
	v_mul_f32_e32 v3, v95, v95
	s_waitcnt lgkmcnt(0)
	v_mul_f32_e32 v4, v89, v89
	v_fmac_f32_e32 v3, v94, v94
	v_fmac_f32_e32 v4, v88, v88
	v_add_f32_e32 v3, v3, v4
	v_mul_f32_e32 v4, v91, v91
	v_mul_f32_e32 v5, v93, v93
	v_fmac_f32_e32 v4, v90, v90
	v_fmac_f32_e32 v5, v92, v92
	v_add_f32_e32 v4, v4, v5
	v_add_f32_e32 v3, v3, v4
	v_mov_b32_e32 v4, v3
	v_mov_b32_e32 v253, v3
	s_nop 1
	v_permlane16_swap_b32 v4, v253
	s_waitcnt lgkmcnt(0)
	v_add_f32_e32 v3, v253, v4
	v_mov_b32_e32 v4, v3
	v_mov_b32_e32 v253, v3
	s_nop 1
	v_permlane32_swap_b32 v4, v253
	s_and_saveexec_b64 s[14:15], vcc
	s_cbranch_execz .LBB0_368
	s_waitcnt lgkmcnt(0)
	v_add_f32_e32 v3, v253, v4
	ds_write_b32 v2, v3 offset:16
.LBB0_368:
	s_or_b64 exec, exec, s[14:15]
	v_mul_f32_e32 v2, v103, v103
	v_mul_f32_e32 v3, v97, v97
	v_fmac_f32_e32 v2, v102, v102
	v_fmac_f32_e32 v3, v96, v96
	v_add_f32_e32 v2, v2, v3
	v_mul_f32_e32 v3, v99, v99
	s_waitcnt lgkmcnt(0)
	v_mul_f32_e32 v4, v101, v101
	v_fmac_f32_e32 v3, v98, v98
	v_fmac_f32_e32 v4, v100, v100
	v_add_f32_e32 v3, v3, v4
	v_add_f32_e32 v2, v2, v3
	v_mov_b32_e32 v3, v2
	v_mov_b32_e32 v253, v2
	s_nop 1
	v_permlane16_swap_b32 v3, v253
	s_waitcnt lgkmcnt(0)
	v_add_f32_e32 v3, v253, v3
	v_mov_b32_e32 v4, v3
	v_mov_b32_e32 v253, v3
	s_nop 1
	v_permlane32_swap_b32 v4, v253
	v_add_u32_e32 v2, s87, v1
	s_and_saveexec_b64 s[14:15], vcc
	s_cbranch_execz .LBB0_370
	s_waitcnt lgkmcnt(0)
	v_add_f32_e32 v3, v253, v4
	ds_write_b32 v2, v3
.LBB0_370:
	s_or_b64 exec, exec, s[14:15]
	v_mul_f32_e32 v3, v119, v119
	s_waitcnt lgkmcnt(0)
	v_mul_f32_e32 v4, v113, v113
	v_fmac_f32_e32 v3, v118, v118
	v_fmac_f32_e32 v4, v112, v112
	v_add_f32_e32 v3, v3, v4
	v_mul_f32_e32 v4, v115, v115
	v_mul_f32_e32 v5, v117, v117
	v_fmac_f32_e32 v4, v114, v114
	v_fmac_f32_e32 v5, v116, v116
	v_add_f32_e32 v4, v4, v5
	v_add_f32_e32 v3, v3, v4
	v_mov_b32_e32 v4, v3
	v_mov_b32_e32 v253, v3
	s_nop 1
	v_permlane16_swap_b32 v4, v253
	s_waitcnt lgkmcnt(0)
	v_add_f32_e32 v3, v253, v4
	v_mov_b32_e32 v4, v3
	v_mov_b32_e32 v253, v3
	s_nop 1
	v_permlane32_swap_b32 v4, v253
	s_and_saveexec_b64 s[14:15], vcc
	s_cbranch_execz .LBB0_372
	s_waitcnt lgkmcnt(0)
	v_add_f32_e32 v3, v253, v4
	ds_write_b32 v2, v3 offset:16
.LBB0_372:
	s_or_b64 exec, exec, s[14:15]
	v_mul_f32_e32 v2, v199, v199
	v_mul_f32_e32 v3, v195, v195
	v_fmac_f32_e32 v2, v198, v198
	v_fmac_f32_e32 v3, v194, v194
	v_add_f32_e32 v2, v2, v3
	v_mul_f32_e32 v3, v197, v197
	s_waitcnt lgkmcnt(0)
	v_mul_f32_e32 v4, v193, v193
	v_fmac_f32_e32 v3, v196, v196
	v_fmac_f32_e32 v4, v192, v192
	v_add_f32_e32 v3, v3, v4
	v_add_f32_e32 v2, v2, v3
	v_mov_b32_e32 v3, v2
	v_mov_b32_e32 v253, v2
	s_nop 1
	v_permlane16_swap_b32 v3, v253
	s_waitcnt lgkmcnt(0)
	v_add_f32_e32 v3, v253, v3
	v_mov_b32_e32 v4, v3
	v_mov_b32_e32 v253, v3
	s_nop 1
	v_permlane32_swap_b32 v4, v253
	v_add_u32_e32 v2, s56, v1
	s_and_saveexec_b64 s[14:15], vcc
	s_cbranch_execz .LBB0_374
	s_waitcnt lgkmcnt(0)
	v_add_f32_e32 v3, v253, v4
	ds_write_b32 v2, v3
.LBB0_374:
	s_or_b64 exec, exec, s[14:15]
	v_mul_f32_e32 v3, v127, v127
	s_waitcnt lgkmcnt(0)
	v_mul_f32_e32 v4, v121, v121
	v_fmac_f32_e32 v3, v126, v126
	v_fmac_f32_e32 v4, v120, v120
	v_add_f32_e32 v3, v3, v4
	v_mul_f32_e32 v4, v123, v123
	v_mul_f32_e32 v5, v125, v125
	v_fmac_f32_e32 v4, v122, v122
	v_fmac_f32_e32 v5, v124, v124
	v_add_f32_e32 v4, v4, v5
	v_add_f32_e32 v3, v3, v4
	v_mov_b32_e32 v4, v3
	v_mov_b32_e32 v253, v3
	s_nop 1
	v_permlane16_swap_b32 v4, v253
	s_waitcnt lgkmcnt(0)
	v_add_f32_e32 v3, v253, v4
	v_mov_b32_e32 v4, v3
	v_mov_b32_e32 v253, v3
	s_nop 1
	v_permlane32_swap_b32 v4, v253
	s_and_saveexec_b64 s[14:15], vcc
	s_cbranch_execz .LBB0_376
	s_waitcnt lgkmcnt(0)
	v_add_f32_e32 v3, v253, v4
	ds_write_b32 v2, v3 offset:16
.LBB0_376:
	s_or_b64 exec, exec, s[14:15]
	v_mul_f32_e32 v2, v191, v191
	v_mul_f32_e32 v3, v187, v187
	v_fmac_f32_e32 v2, v190, v190
	v_fmac_f32_e32 v3, v186, v186
	v_add_f32_e32 v2, v2, v3
	v_mul_f32_e32 v3, v189, v189
	s_waitcnt lgkmcnt(0)
	v_mul_f32_e32 v4, v185, v185
	v_fmac_f32_e32 v3, v188, v188
	v_fmac_f32_e32 v4, v184, v184
	v_add_f32_e32 v3, v3, v4
	v_add_f32_e32 v2, v2, v3
	v_mov_b32_e32 v3, v2
	v_mov_b32_e32 v253, v2
	s_nop 1
	v_permlane16_swap_b32 v3, v253
	s_waitcnt lgkmcnt(0)
	v_add_f32_e32 v3, v253, v3
	v_mov_b32_e32 v4, v3
	v_mov_b32_e32 v253, v3
	s_nop 1
	v_permlane32_swap_b32 v4, v253
	v_add_u32_e32 v2, s96, v1
	s_and_saveexec_b64 s[14:15], vcc
	s_cbranch_execz .LBB0_378
	s_waitcnt lgkmcnt(0)
	v_add_f32_e32 v3, v253, v4
	ds_write_b32 v2, v3
.LBB0_378:
	s_or_b64 exec, exec, s[14:15]
	v_mul_f32_e32 v3, v135, v135
	s_waitcnt lgkmcnt(0)
	v_mul_f32_e32 v4, v129, v129
	v_fmac_f32_e32 v3, v134, v134
	v_fmac_f32_e32 v4, v128, v128
	v_add_f32_e32 v3, v3, v4
	v_mul_f32_e32 v4, v131, v131
	v_mul_f32_e32 v5, v133, v133
	v_fmac_f32_e32 v4, v130, v130
	v_fmac_f32_e32 v5, v132, v132
	v_add_f32_e32 v4, v4, v5
	v_add_f32_e32 v3, v3, v4
	v_mov_b32_e32 v4, v3
	v_mov_b32_e32 v253, v3
	s_nop 1
	v_permlane16_swap_b32 v4, v253
	s_waitcnt lgkmcnt(0)
	v_add_f32_e32 v3, v253, v4
	v_mov_b32_e32 v4, v3
	v_mov_b32_e32 v253, v3
	s_nop 1
	v_permlane32_swap_b32 v4, v253
	s_and_saveexec_b64 s[14:15], vcc
	s_cbranch_execz .LBB0_380
	s_waitcnt lgkmcnt(0)
	v_add_f32_e32 v3, v253, v4
	ds_write_b32 v2, v3 offset:16
.LBB0_380:
	s_or_b64 exec, exec, s[14:15]
	v_mul_f32_e32 v2, v183, v183
	v_mul_f32_e32 v3, v179, v179
	v_fmac_f32_e32 v2, v182, v182
	v_fmac_f32_e32 v3, v178, v178
	v_add_f32_e32 v2, v2, v3
	v_mul_f32_e32 v3, v181, v181
	s_waitcnt lgkmcnt(0)
	v_mul_f32_e32 v4, v177, v177
	v_fmac_f32_e32 v3, v180, v180
	v_fmac_f32_e32 v4, v176, v176
	v_add_f32_e32 v3, v3, v4
	v_add_f32_e32 v2, v2, v3
	v_mov_b32_e32 v3, v2
	v_mov_b32_e32 v253, v2
	s_nop 1
	v_permlane16_swap_b32 v3, v253
	s_waitcnt lgkmcnt(0)
	v_add_f32_e32 v3, v253, v3
	v_mov_b32_e32 v4, v3
	v_mov_b32_e32 v253, v3
	s_nop 1
	v_permlane32_swap_b32 v4, v253
	v_add_u32_e32 v2, s58, v1
	s_and_saveexec_b64 s[14:15], vcc
	s_cbranch_execz .LBB0_382
	s_waitcnt lgkmcnt(0)
	v_add_f32_e32 v3, v253, v4
	ds_write_b32 v2, v3
.LBB0_382:
	s_or_b64 exec, exec, s[14:15]
	v_mul_f32_e32 v3, v143, v143
	s_waitcnt lgkmcnt(0)
	v_mul_f32_e32 v4, v137, v137
	v_fmac_f32_e32 v3, v142, v142
	v_fmac_f32_e32 v4, v136, v136
	v_add_f32_e32 v3, v3, v4
	v_mul_f32_e32 v4, v139, v139
	v_mul_f32_e32 v5, v141, v141
	v_fmac_f32_e32 v4, v138, v138
	v_fmac_f32_e32 v5, v140, v140
	v_add_f32_e32 v4, v4, v5
	v_add_f32_e32 v3, v3, v4
	v_mov_b32_e32 v4, v3
	v_mov_b32_e32 v253, v3
	s_nop 1
	v_permlane16_swap_b32 v4, v253
	s_waitcnt lgkmcnt(0)
	v_add_f32_e32 v3, v253, v4
	v_mov_b32_e32 v4, v3
	v_mov_b32_e32 v253, v3
	s_nop 1
	v_permlane32_swap_b32 v4, v253
	s_and_saveexec_b64 s[14:15], vcc
	s_cbranch_execz .LBB0_384
	s_waitcnt lgkmcnt(0)
	v_add_f32_e32 v3, v253, v4
	ds_write_b32 v2, v3 offset:16
.LBB0_384:
	s_or_b64 exec, exec, s[14:15]
	v_mul_f32_e32 v2, v167, v167
	v_mul_f32_e32 v3, v163, v163
	v_fmac_f32_e32 v2, v166, v166
	v_fmac_f32_e32 v3, v162, v162
	v_add_f32_e32 v2, v2, v3
	v_mul_f32_e32 v3, v165, v165
	s_waitcnt lgkmcnt(0)
	v_mul_f32_e32 v4, v161, v161
	v_fmac_f32_e32 v3, v164, v164
	v_fmac_f32_e32 v4, v160, v160
	v_add_f32_e32 v3, v3, v4
	v_add_f32_e32 v2, v2, v3
	v_mov_b32_e32 v3, v2
	v_mov_b32_e32 v253, v2
	s_nop 1
	v_permlane16_swap_b32 v3, v253
	v_add_u32_e32 v1, s59, v1
	s_waitcnt lgkmcnt(0)
	v_add_f32_e32 v2, v253, v3
	v_mov_b32_e32 v3, v2
	v_mov_b32_e32 v253, v2
	s_nop 1
	v_permlane32_swap_b32 v3, v253
	s_and_saveexec_b64 s[14:15], vcc
	s_cbranch_execz .LBB0_386
	s_waitcnt lgkmcnt(0)
	v_add_f32_e32 v2, v253, v3
	ds_write_b32 v1, v2
.LBB0_386:
	s_or_b64 exec, exec, s[14:15]
	v_mul_f32_e32 v2, v173, v173
	s_waitcnt lgkmcnt(0)
	v_mul_f32_e32 v3, v171, v171
	v_fmac_f32_e32 v2, v172, v172
	v_fmac_f32_e32 v3, v170, v170
	v_add_f32_e32 v2, v2, v3
	v_mul_f32_e32 v3, v175, v175
	v_mul_f32_e32 v4, v169, v169
	v_fmac_f32_e32 v3, v174, v174
	v_fmac_f32_e32 v4, v168, v168
	v_add_f32_e32 v3, v3, v4
	v_add_f32_e32 v2, v2, v3
	v_mov_b32_e32 v0, v2
	v_mov_b32_e32 v253, v2
	s_nop 1
	v_permlane16_swap_b32 v0, v253
	s_waitcnt lgkmcnt(0)
	v_add_f32_e32 v0, v253, v0
	v_mov_b32_e32 v2, v0
	v_mov_b32_e32 v253, v0
	s_nop 1
	v_permlane32_swap_b32 v2, v253
	s_and_saveexec_b64 s[14:15], vcc
	s_cbranch_execz .LBB0_388
	s_waitcnt lgkmcnt(0)
	v_add_f32_e32 v0, v253, v2
	ds_write_b32 v1, v0 offset:16

.LBB0_753:
	v_mbcnt_lo_u32_b32 v242, -1, 0
	v_mbcnt_hi_u32_b32 v242, -1, v242
	v_bfe_u32 v242, v242, 4, 1
	v_mul_u32_u24_e32 v242, 24, v242
	v_mov_b32_e32 v243, 0
	v_lshl_or_b32 v140, s42, 8, v186
	v_lshl_add_u32 v144, s40, 8, v182
	v_ashrrev_i32_e32 v141, 31, v140
	v_lshlrev_b64 v[190:191], 1, v[140:141]
	v_ashrrev_i32_e32 v145, 31, v144
	v_lshl_add_u64 v[142:143], s[34:35], 0, v[190:191]
	v_lshlrev_b64 v[192:193], 12, v[144:145]
	v_lshl_add_u64 v[146:147], v[142:143], 0, v[192:193]
	v_lshl_add_u64 v[252:253], v[146:147], 0, v[242:243]
	global_load_dwordx4 v[208:211], v[252:253], off
	v_lshl_add_u64 v[252:253], v[146:147], 0, v[242:243]
	global_load_dwordx4 v[212:215], v[252:253], off offset:256
	v_or_b32_e32 v162, 16, v144
	v_or_b32_e32 v150, 32, v144
	v_or_b32_e32 v146, 48, v144
	v_ashrrev_i32_e32 v163, 31, v162
	v_ashrrev_i32_e32 v151, 31, v150
	v_ashrrev_i32_e32 v147, 31, v146
	v_lshlrev_b64 v[172:173], 12, v[162:163]
	v_lshlrev_b64 v[160:161], 12, v[150:151]
	v_lshlrev_b64 v[148:149], 12, v[146:147]
	v_lshl_add_u64 v[152:153], v[142:143], 0, v[172:173]
	v_lshl_add_u64 v[154:155], v[142:143], 0, v[160:161]
	v_lshl_add_u64 v[202:203], v[142:143], 0, v[148:149]
	v_lshl_add_u64 v[252:253], v[152:153], 0, v[242:243]
	global_load_dwordx4 v[216:219], v[252:253], off
	v_lshl_add_u64 v[252:253], v[152:153], 0, v[242:243]
	global_load_dwordx4 v[220:223], v[252:253], off offset:256
	v_lshl_add_u64 v[252:253], v[154:155], 0, v[242:243]
	global_load_dwordx4 v[224:227], v[252:253], off
	v_lshl_add_u64 v[252:253], v[154:155], 0, v[242:243]
	global_load_dwordx4 v[228:231], v[252:253], off offset:256
	v_lshl_add_u64 v[252:253], v[202:203], 0, v[242:243]
	global_load_dwordx4 v[244:247], v[252:253], off
	s_nop 0
	v_lshl_add_u64 v[252:253], v[202:203], 0, v[242:243]
	global_load_dwordx4 v[248:251], v[252:253], off offset:256
	v_lshl_add_u64 v[192:193], s[34:35], 0, v[192:193]
	v_lshl_add_u64 v[190:191], v[192:193], 0, v[190:191]
	s_waitcnt vmcnt(0)
	v_permlane16_swap_b32 v208, v210
	v_permlane16_swap_b32 v209, v211
	v_lshlrev_b32_e32 v192, 16, v208
	v_and_b32_e32 v193, 0xffff0000, v208
	v_lshlrev_b32_e32 v194, 16, v209
	v_and_b32_e32 v195, 0xffff0000, v209
	v_lshlrev_b32_e32 v202, 16, v210
	v_and_b32_e32 v203, 0xffff0000, v210
	v_lshlrev_b32_e32 v196, 16, v211
	v_and_b32_e32 v197, 0xffff0000, v211
	v_permlane16_swap_b32 v212, v214
	v_permlane16_swap_b32 v213, v215
	v_lshlrev_b32_e32 v204, 16, v212
	v_and_b32_e32 v205, 0xffff0000, v212
	v_lshlrev_b32_e32 v198, 16, v213
	v_and_b32_e32 v199, 0xffff0000, v213
	v_lshlrev_b32_e32 v206, 16, v214
	v_and_b32_e32 v207, 0xffff0000, v214
	v_pk_add_f32 v[126:127], v[126:127], v[194:195]
	v_pk_add_f32 v[124:125], v[124:125], v[192:193]
	v_pk_add_f32 v[122:123], v[122:123], v[196:197]
	v_pk_add_f32 v[120:121], v[120:121], v[202:203]
	v_lshlrev_b32_e32 v200, 16, v215
	v_and_b32_e32 v201, 0xffff0000, v215
	v_pk_add_f32 v[118:119], v[118:119], v[198:199]
	v_pk_add_f32 v[116:117], v[116:117], v[204:205]
	v_pk_add_f32 v[192:193], v[112:113], v[206:207]
	v_mul_f32_e32 v194, v125, v125
	v_mul_f32_e32 v195, v127, v127
	v_cvt_pk_bf16_f32 v232, v124, v125
	v_cvt_pk_bf16_f32 v233, v126, v127
	v_mul_f32_e32 v125, v121, v121
	v_mul_f32_e32 v127, v123, v123
	v_pk_add_f32 v[114:115], v[114:115], v[200:201]
	v_mul_f32_e32 v196, v117, v117
	v_mul_f32_e32 v197, v119, v119
	v_fmac_f32_e32 v194, v124, v124
	v_fmac_f32_e32 v195, v126, v126
	v_fmac_f32_e32 v125, v120, v120
	v_fmac_f32_e32 v127, v122, v122
	v_mul_f32_e32 v198, v193, v193
	v_mul_f32_e32 v199, v115, v115
	v_cvt_pk_bf16_f32 v234, v120, v121
	v_fmac_f32_e32 v196, v116, v116
	v_fmac_f32_e32 v197, v118, v118
	v_add_f32_e32 v113, v194, v195
	v_add_f32_e32 v120, v125, v127
	v_fmac_f32_e32 v198, v192, v192
	v_fmac_f32_e32 v199, v114, v114
	v_add_f32_e32 v121, v196, v197
	v_add_f32_e32 v113, v113, v120
	v_add_f32_e32 v113, v113, v121
	v_add_f32_e32 v120, v198, v199
	v_add_f32_e32 v120, v113, v120
	v_mov_b32_e32 v121, v120
	v_mov_b32_e32 v254, v120
	s_nop 1
	v_permlane16_swap_b32 v121, v254
	v_cvt_pk_bf16_f32 v235, v122, v123
	s_nop 1
	v_permlane16_swap_b32 v232, v234
	v_permlane16_swap_b32 v233, v235
	v_lshl_add_u64 v[240:241], v[190:191], 0, v[242:243]
	global_store_dwordx4 v[240:241], v[232:235], off
	v_cvt_pk_bf16_f32 v236, v116, v117
	v_cvt_pk_bf16_f32 v237, v118, v119
	s_waitcnt lgkmcnt(0)
	v_add_f32_e32 v112, v254, v121
	v_mov_b32_e32 v113, v112
	v_mov_b32_e32 v254, v112
	s_nop 1
	v_permlane32_swap_b32 v113, v254
	v_cvt_pk_bf16_f32 v238, v192, v193
	v_cvt_pk_bf16_f32 v239, v114, v115
	s_nop 1
	v_permlane16_swap_b32 v236, v238
	v_permlane16_swap_b32 v237, v239
	v_lshl_add_u64 v[240:241], v[190:191], 0, v[242:243]
	global_store_dwordx4 v[240:241], v[236:239], off offset:256
	s_and_saveexec_b64 s[40:41], s[8:9]
	s_cbranch_execz .LBB0_755
	v_lshl_add_u64 v[114:115], v[144:145], 2, s[12:13]
	s_waitcnt lgkmcnt(0)
	v_add_f32_e32 v112, v254, v113
	global_atomic_add_f32 v[114:115], v112, off
.LBB0_755:
	s_or_b64 exec, exec, s[40:41]
	v_permlane16_swap_b32 v216, v218
	v_permlane16_swap_b32 v217, v219
	v_lshlrev_b32_e32 v112, 16, v216
	s_waitcnt lgkmcnt(0)
	v_and_b32_e32 v113, 0xffff0000, v216
	v_lshlrev_b32_e32 v114, 16, v217
	v_and_b32_e32 v115, 0xffff0000, v217
	v_pk_add_f32 v[110:111], v[110:111], v[114:115]
	v_pk_add_f32 v[108:109], v[108:109], v[112:113]
	v_mul_f32_e32 v113, v111, v111
	v_mul_f32_e32 v112, v109, v109
	v_lshlrev_b32_e32 v116, 16, v218
	v_and_b32_e32 v117, 0xffff0000, v218
	v_lshlrev_b32_e32 v118, 16, v219
	v_and_b32_e32 v119, 0xffff0000, v219
	v_fmac_f32_e32 v112, v108, v108
	v_fmac_f32_e32 v113, v110, v110
	v_cvt_pk_bf16_f32 v232, v108, v109
	v_cvt_pk_bf16_f32 v233, v110, v111
	v_lshl_add_u64 v[110:111], s[34:35], 0, v[172:173]
	v_lshl_add_u64 v[110:111], v[140:141], 1, v[110:111]
	v_pk_add_f32 v[106:107], v[106:107], v[118:119]
	v_pk_add_f32 v[104:105], v[104:105], v[116:117]
	v_permlane16_swap_b32 v220, v222
	v_permlane16_swap_b32 v221, v223
	v_lshlrev_b32_e32 v120, 16, v220
	v_and_b32_e32 v121, 0xffff0000, v220
	v_lshlrev_b32_e32 v122, 16, v221
	v_and_b32_e32 v123, 0xffff0000, v221
	v_mul_f32_e32 v108, v105, v105
	v_mul_f32_e32 v109, v107, v107
	v_fmac_f32_e32 v108, v104, v104
	v_fmac_f32_e32 v109, v106, v106
	v_pk_add_f32 v[102:103], v[102:103], v[122:123]
	v_pk_add_f32 v[100:101], v[100:101], v[120:121]
	v_add_f32_e32 v108, v108, v109
	v_cvt_pk_bf16_f32 v234, v104, v105
	v_mul_f32_e32 v105, v101, v101
	v_mul_f32_e32 v109, v103, v103
	v_add_f32_e32 v112, v112, v113
	v_fmac_f32_e32 v105, v100, v100
	v_fmac_f32_e32 v109, v102, v102
	v_lshlrev_b32_e32 v124, 16, v222
	v_and_b32_e32 v125, 0xffff0000, v222
	v_lshlrev_b32_e32 v126, 16, v223
	v_and_b32_e32 v127, 0xffff0000, v223
	v_add_f32_e32 v108, v112, v108
	v_add_f32_e32 v105, v105, v109
	v_add_f32_e32 v105, v108, v105
	v_pk_add_f32 v[98:99], v[98:99], v[126:127]
	v_pk_add_f32 v[108:109], v[96:97], v[124:125]
	v_mul_f32_e32 v97, v99, v99
	v_mul_f32_e32 v96, v109, v109
	v_fmac_f32_e32 v96, v108, v108
	v_fmac_f32_e32 v97, v98, v98
	v_add_f32_e32 v96, v96, v97
	v_add_f32_e32 v96, v105, v96
	v_mov_b32_e32 v97, v96
	v_mov_b32_e32 v254, v96
	s_nop 1
	v_permlane16_swap_b32 v97, v254
	v_cvt_pk_bf16_f32 v235, v106, v107
	s_nop 1
	v_permlane16_swap_b32 v232, v234
	v_permlane16_swap_b32 v233, v235
	v_lshl_add_u64 v[240:241], v[110:111], 0, v[242:243]
	global_store_dwordx4 v[240:241], v[232:235], off
	v_cvt_pk_bf16_f32 v236, v100, v101
	v_cvt_pk_bf16_f32 v237, v102, v103
	s_waitcnt lgkmcnt(0)
	v_add_f32_e32 v96, v254, v97
	v_mov_b32_e32 v97, v96
	v_mov_b32_e32 v254, v96
	s_nop 1
	v_permlane32_swap_b32 v97, v254
	v_cvt_pk_bf16_f32 v238, v108, v109
	v_cvt_pk_bf16_f32 v239, v98, v99
	s_nop 1
	v_permlane16_swap_b32 v236, v238
	v_permlane16_swap_b32 v237, v239
	v_lshl_add_u64 v[240:241], v[110:111], 0, v[242:243]
	global_store_dwordx4 v[240:241], v[236:239], off offset:256
	s_and_saveexec_b64 s[40:41], s[8:9]
	s_cbranch_execz .LBB0_757
	v_lshl_add_u64 v[98:99], v[162:163], 2, s[12:13]
	s_waitcnt lgkmcnt(0)
	v_add_f32_e32 v96, v254, v97
	global_atomic_add_f32 v[98:99], v96, off
.LBB0_757:
	s_or_b64 exec, exec, s[40:41]
	v_permlane16_swap_b32 v224, v226
	v_permlane16_swap_b32 v225, v227
	v_lshlrev_b32_e32 v96, 16, v224
	s_waitcnt lgkmcnt(0)
	v_and_b32_e32 v97, 0xffff0000, v224
	v_lshlrev_b32_e32 v98, 16, v225
	v_and_b32_e32 v99, 0xffff0000, v225
	v_pk_add_f32 v[94:95], v[94:95], v[98:99]
	v_pk_add_f32 v[92:93], v[92:93], v[96:97]
	v_mul_f32_e32 v97, v95, v95
	v_mul_f32_e32 v96, v93, v93
	v_lshlrev_b32_e32 v100, 16, v226
	v_and_b32_e32 v101, 0xffff0000, v226
	v_lshlrev_b32_e32 v102, 16, v227
	v_and_b32_e32 v103, 0xffff0000, v227
	v_fmac_f32_e32 v96, v92, v92
	v_fmac_f32_e32 v97, v94, v94
	v_cvt_pk_bf16_f32 v232, v92, v93
	v_cvt_pk_bf16_f32 v233, v94, v95
	v_lshl_add_u64 v[94:95], s[34:35], 0, v[160:161]
	v_lshl_add_u64 v[94:95], v[140:141], 1, v[94:95]
	v_pk_add_f32 v[90:91], v[90:91], v[102:103]
	v_pk_add_f32 v[88:89], v[88:89], v[100:101]
	v_permlane16_swap_b32 v228, v230
	v_permlane16_swap_b32 v229, v231
	v_lshlrev_b32_e32 v104, 16, v228
	v_and_b32_e32 v105, 0xffff0000, v228
	v_lshlrev_b32_e32 v106, 16, v229
	v_and_b32_e32 v107, 0xffff0000, v229
	v_mul_f32_e32 v92, v89, v89
	v_mul_f32_e32 v93, v91, v91
	v_fmac_f32_e32 v92, v88, v88
	v_fmac_f32_e32 v93, v90, v90
	v_pk_add_f32 v[86:87], v[86:87], v[106:107]
	v_pk_add_f32 v[84:85], v[84:85], v[104:105]
	v_add_f32_e32 v92, v92, v93
	v_cvt_pk_bf16_f32 v234, v88, v89
	v_mul_f32_e32 v89, v85, v85
	v_mul_f32_e32 v93, v87, v87
	v_add_f32_e32 v96, v96, v97
	v_fmac_f32_e32 v89, v84, v84
	v_fmac_f32_e32 v93, v86, v86
	v_lshlrev_b32_e32 v108, 16, v230
	v_and_b32_e32 v109, 0xffff0000, v230
	v_lshlrev_b32_e32 v110, 16, v231
	v_and_b32_e32 v111, 0xffff0000, v231
	v_add_f32_e32 v92, v96, v92
	v_add_f32_e32 v89, v89, v93
	v_add_f32_e32 v89, v92, v89
	v_pk_add_f32 v[82:83], v[82:83], v[110:111]
	v_pk_add_f32 v[92:93], v[80:81], v[108:109]
	v_mul_f32_e32 v81, v83, v83
	v_mul_f32_e32 v80, v93, v93
	v_fmac_f32_e32 v80, v92, v92
	v_fmac_f32_e32 v81, v82, v82
	v_add_f32_e32 v80, v80, v81
	v_add_f32_e32 v80, v89, v80
	v_mov_b32_e32 v81, v80
	v_mov_b32_e32 v254, v80
	s_nop 1
	v_permlane16_swap_b32 v81, v254
	v_cvt_pk_bf16_f32 v235, v90, v91
	s_nop 1
	v_permlane16_swap_b32 v232, v234
	v_permlane16_swap_b32 v233, v235
	v_lshl_add_u64 v[240:241], v[94:95], 0, v[242:243]
	global_store_dwordx4 v[240:241], v[232:235], off
	v_cvt_pk_bf16_f32 v236, v84, v85
	v_cvt_pk_bf16_f32 v237, v86, v87
	s_waitcnt lgkmcnt(0)
	v_add_f32_e32 v80, v254, v81
	v_mov_b32_e32 v81, v80
	v_mov_b32_e32 v254, v80
	s_nop 1
	v_permlane32_swap_b32 v81, v254
	v_cvt_pk_bf16_f32 v238, v92, v93
	v_cvt_pk_bf16_f32 v239, v82, v83
	s_nop 1
	v_permlane16_swap_b32 v236, v238
	v_permlane16_swap_b32 v237, v239
	v_lshl_add_u64 v[240:241], v[94:95], 0, v[242:243]
	global_store_dwordx4 v[240:241], v[236:239], off offset:256
	s_and_saveexec_b64 s[40:41], s[8:9]
	s_cbranch_execz .LBB0_759
	v_lshl_add_u64 v[82:83], v[150:151], 2, s[12:13]
	s_waitcnt lgkmcnt(0)
	v_add_f32_e32 v80, v254, v81
	global_atomic_add_f32 v[82:83], v80, off
.LBB0_759:
	s_or_b64 exec, exec, s[40:41]
	v_permlane16_swap_b32 v244, v246
	v_permlane16_swap_b32 v245, v247
	v_lshlrev_b32_e32 v80, 16, v244
	s_waitcnt lgkmcnt(0)
	v_and_b32_e32 v81, 0xffff0000, v244
	v_lshlrev_b32_e32 v82, 16, v245
	v_and_b32_e32 v83, 0xffff0000, v245
	v_pk_add_f32 v[78:79], v[78:79], v[82:83]
	v_pk_add_f32 v[76:77], v[76:77], v[80:81]
	v_mul_f32_e32 v81, v79, v79
	v_mul_f32_e32 v80, v77, v77
	v_lshlrev_b32_e32 v84, 16, v246
	v_and_b32_e32 v85, 0xffff0000, v246
	v_lshlrev_b32_e32 v86, 16, v247
	v_and_b32_e32 v87, 0xffff0000, v247
	v_fmac_f32_e32 v80, v76, v76
	v_fmac_f32_e32 v81, v78, v78
	v_cvt_pk_bf16_f32 v232, v76, v77
	v_cvt_pk_bf16_f32 v233, v78, v79
	v_lshl_add_u64 v[78:79], s[34:35], 0, v[148:149]
	v_lshl_add_u64 v[78:79], v[140:141], 1, v[78:79]
	v_pk_add_f32 v[74:75], v[74:75], v[86:87]
	v_pk_add_f32 v[72:73], v[72:73], v[84:85]
	v_permlane16_swap_b32 v248, v250
	v_permlane16_swap_b32 v249, v251
	v_lshlrev_b32_e32 v88, 16, v248
	v_and_b32_e32 v89, 0xffff0000, v248
	v_lshlrev_b32_e32 v90, 16, v249
	v_and_b32_e32 v91, 0xffff0000, v249
	v_mul_f32_e32 v76, v73, v73
	v_mul_f32_e32 v77, v75, v75
	v_fmac_f32_e32 v76, v72, v72
	v_fmac_f32_e32 v77, v74, v74
	v_pk_add_f32 v[70:71], v[70:71], v[90:91]
	v_pk_add_f32 v[68:69], v[68:69], v[88:89]
	v_add_f32_e32 v76, v76, v77
	v_cvt_pk_bf16_f32 v234, v72, v73
	v_mul_f32_e32 v73, v69, v69
	v_mul_f32_e32 v77, v71, v71
	v_add_f32_e32 v80, v80, v81
	v_fmac_f32_e32 v73, v68, v68
	v_fmac_f32_e32 v77, v70, v70
	v_lshlrev_b32_e32 v92, 16, v250
	v_and_b32_e32 v93, 0xffff0000, v250
	v_lshlrev_b32_e32 v94, 16, v251
	v_and_b32_e32 v95, 0xffff0000, v251
	v_add_f32_e32 v76, v80, v76
	v_add_f32_e32 v73, v73, v77
	v_add_f32_e32 v73, v76, v73
	v_pk_add_f32 v[66:67], v[66:67], v[94:95]
	v_pk_add_f32 v[76:77], v[64:65], v[92:93]
	v_mul_f32_e32 v65, v67, v67
	v_mul_f32_e32 v64, v77, v77
	v_fmac_f32_e32 v64, v76, v76
	v_fmac_f32_e32 v65, v66, v66
	v_add_f32_e32 v64, v64, v65
	v_add_f32_e32 v64, v73, v64
	v_mov_b32_e32 v65, v64
	v_mov_b32_e32 v254, v64
	s_nop 1
	v_permlane16_swap_b32 v65, v254
	v_cvt_pk_bf16_f32 v235, v74, v75
	s_nop 1
	v_permlane16_swap_b32 v232, v234
	v_permlane16_swap_b32 v233, v235
	v_lshl_add_u64 v[240:241], v[78:79], 0, v[242:243]
	global_store_dwordx4 v[240:241], v[232:235], off
	v_cvt_pk_bf16_f32 v236, v68, v69
	v_cvt_pk_bf16_f32 v237, v70, v71
	s_waitcnt lgkmcnt(0)
	v_add_f32_e32 v64, v254, v65
	v_mov_b32_e32 v65, v64
	v_mov_b32_e32 v254, v64
	s_nop 1
	v_permlane32_swap_b32 v65, v254
	v_cvt_pk_bf16_f32 v238, v76, v77
	v_cvt_pk_bf16_f32 v239, v66, v67
	s_nop 1
	v_permlane16_swap_b32 v236, v238
	v_permlane16_swap_b32 v237, v239
	v_lshl_add_u64 v[240:241], v[78:79], 0, v[242:243]
	global_store_dwordx4 v[240:241], v[236:239], off offset:256
	s_and_saveexec_b64 s[40:41], s[8:9]
	s_cbranch_execz .LBB0_761
	v_lshl_add_u64 v[66:67], v[146:147], 2, s[12:13]
	s_waitcnt lgkmcnt(0)
	v_add_f32_e32 v64, v254, v65
	global_atomic_add_f32 v[66:67], v64, off
.LBB0_761:
	s_or_b64 exec, exec, s[40:41]
	v_add_u32_e32 v90, 0x80, v144
	v_ashrrev_i32_e32 v91, 31, v90
	v_lshlrev_b64 v[102:103], 12, v[90:91]
	s_waitcnt lgkmcnt(0)
	v_lshl_add_u64 v[64:65], v[142:143], 0, v[102:103]
	v_lshl_add_u64 v[252:253], v[64:65], 0, v[242:243]
	global_load_dwordx4 v[208:211], v[252:253], off
	v_lshl_add_u64 v[252:253], v[64:65], 0, v[242:243]
	global_load_dwordx4 v[212:215], v[252:253], off offset:256
	v_add_u32_e32 v80, 0x90, v144
	v_add_u32_e32 v68, 0xa0, v144
	v_add_u32_e32 v64, 0xb0, v144
	v_ashrrev_i32_e32 v81, 31, v80
	v_ashrrev_i32_e32 v69, 31, v68
	v_ashrrev_i32_e32 v65, 31, v64
	v_lshlrev_b64 v[92:93], 12, v[80:81]
	v_lshlrev_b64 v[78:79], 12, v[68:69]
	v_lshlrev_b64 v[66:67], 12, v[64:65]
	v_lshl_add_u64 v[70:71], v[142:143], 0, v[92:93]
	v_lshl_add_u64 v[72:73], v[142:143], 0, v[78:79]
	v_lshl_add_u64 v[112:113], v[142:143], 0, v[66:67]
	v_lshl_add_u64 v[252:253], v[70:71], 0, v[242:243]
	global_load_dwordx4 v[216:219], v[252:253], off
	v_lshl_add_u64 v[252:253], v[70:71], 0, v[242:243]
	global_load_dwordx4 v[220:223], v[252:253], off offset:256
	v_lshl_add_u64 v[252:253], v[72:73], 0, v[242:243]
	global_load_dwordx4 v[224:227], v[252:253], off
	v_lshl_add_u64 v[252:253], v[72:73], 0, v[242:243]
	global_load_dwordx4 v[228:231], v[252:253], off offset:256
	v_lshl_add_u64 v[252:253], v[112:113], 0, v[242:243]
	global_load_dwordx4 v[244:247], v[252:253], off
	s_nop 0
	v_lshl_add_u64 v[252:253], v[112:113], 0, v[242:243]
	global_load_dwordx4 v[248:251], v[252:253], off offset:256
	v_lshl_add_u64 v[102:103], s[34:35], 0, v[102:103]
	v_lshl_add_u64 v[102:103], v[140:141], 1, v[102:103]
	s_waitcnt vmcnt(7)
	v_permlane16_swap_b32 v208, v210
	v_permlane16_swap_b32 v209, v211
	v_lshlrev_b32_e32 v112, 16, v208
	v_and_b32_e32 v113, 0xffff0000, v208
	v_lshlrev_b32_e32 v104, 16, v209
	v_and_b32_e32 v105, 0xffff0000, v209
	s_waitcnt vmcnt(7)
	v_lshlrev_b32_e32 v114, 16, v210
	v_and_b32_e32 v115, 0xffff0000, v210
	v_lshlrev_b32_e32 v106, 16, v211
	v_and_b32_e32 v107, 0xffff0000, v211
	s_waitcnt vmcnt(6)
	v_permlane16_swap_b32 v212, v214
	v_permlane16_swap_b32 v213, v215
	v_lshlrev_b32_e32 v116, 16, v212
	v_and_b32_e32 v117, 0xffff0000, v212
	v_lshlrev_b32_e32 v108, 16, v213
	v_and_b32_e32 v109, 0xffff0000, v213
	s_waitcnt vmcnt(6)
	v_lshlrev_b32_e32 v118, 16, v214
	v_and_b32_e32 v119, 0xffff0000, v214
	v_pk_add_f32 v[62:63], v[62:63], v[104:105]
	v_pk_add_f32 v[60:61], v[60:61], v[112:113]
	v_pk_add_f32 v[58:59], v[58:59], v[106:107]
	v_pk_add_f32 v[56:57], v[56:57], v[114:115]
	v_lshlrev_b32_e32 v110, 16, v215
	v_and_b32_e32 v111, 0xffff0000, v215
	v_pk_add_f32 v[54:55], v[54:55], v[108:109]
	v_pk_add_f32 v[52:53], v[52:53], v[116:117]
	v_pk_add_f32 v[104:105], v[48:49], v[118:119]
	v_mul_f32_e32 v106, v61, v61
	v_mul_f32_e32 v107, v63, v63
	v_cvt_pk_bf16_f32 v232, v60, v61
	v_cvt_pk_bf16_f32 v233, v62, v63
	v_mul_f32_e32 v61, v57, v57
	v_mul_f32_e32 v63, v59, v59
	v_pk_add_f32 v[50:51], v[50:51], v[110:111]
	v_mul_f32_e32 v108, v53, v53
	v_mul_f32_e32 v109, v55, v55
	v_fmac_f32_e32 v106, v60, v60
	v_fmac_f32_e32 v107, v62, v62
	v_fmac_f32_e32 v61, v56, v56
	v_fmac_f32_e32 v63, v58, v58
	v_mul_f32_e32 v110, v105, v105
	v_mul_f32_e32 v111, v51, v51
	v_cvt_pk_bf16_f32 v234, v56, v57
	v_fmac_f32_e32 v108, v52, v52
	v_fmac_f32_e32 v109, v54, v54
	v_add_f32_e32 v49, v106, v107
	v_add_f32_e32 v56, v61, v63
	v_fmac_f32_e32 v110, v104, v104
	v_fmac_f32_e32 v111, v50, v50
	v_add_f32_e32 v57, v108, v109
	v_add_f32_e32 v49, v49, v56
	v_add_f32_e32 v49, v49, v57
	v_add_f32_e32 v56, v110, v111
	v_add_f32_e32 v56, v49, v56
	v_mov_b32_e32 v57, v56
	v_mov_b32_e32 v254, v56
	s_nop 1
	v_permlane16_swap_b32 v57, v254
	v_cvt_pk_bf16_f32 v235, v58, v59
	s_nop 1
	v_permlane16_swap_b32 v232, v234
	v_permlane16_swap_b32 v233, v235
	v_lshl_add_u64 v[240:241], v[102:103], 0, v[242:243]
	global_store_dwordx4 v[240:241], v[232:235], off
	v_cvt_pk_bf16_f32 v236, v52, v53
	v_cvt_pk_bf16_f32 v237, v54, v55
	s_waitcnt lgkmcnt(0)
	v_add_f32_e32 v48, v254, v57
	v_mov_b32_e32 v49, v48
	v_mov_b32_e32 v254, v48
	s_nop 1
	v_permlane32_swap_b32 v49, v254
	v_cvt_pk_bf16_f32 v238, v104, v105
	v_cvt_pk_bf16_f32 v239, v50, v51
	s_nop 1
	v_permlane16_swap_b32 v236, v238
	v_permlane16_swap_b32 v237, v239
	v_lshl_add_u64 v[240:241], v[102:103], 0, v[242:243]
	global_store_dwordx4 v[240:241], v[236:239], off offset:256
	s_and_saveexec_b64 s[40:41], s[8:9]
	s_cbranch_execz .LBB0_763
	v_lshl_add_u64 v[50:51], v[90:91], 2, s[12:13]
	s_waitcnt lgkmcnt(0)
	v_add_f32_e32 v48, v254, v49
	global_atomic_add_f32 v[50:51], v48, off
.LBB0_763:
	s_or_b64 exec, exec, s[40:41]
	s_waitcnt vmcnt(7)
	v_permlane16_swap_b32 v216, v218
	v_permlane16_swap_b32 v217, v219
	v_lshlrev_b32_e32 v48, 16, v216
	s_waitcnt lgkmcnt(0)
	v_and_b32_e32 v49, 0xffff0000, v216
	v_lshlrev_b32_e32 v50, 16, v217
	v_and_b32_e32 v51, 0xffff0000, v217
	v_pk_add_f32 v[46:47], v[46:47], v[50:51]
	v_pk_add_f32 v[44:45], v[44:45], v[48:49]
	v_mul_f32_e32 v49, v47, v47
	v_mul_f32_e32 v48, v45, v45
	s_waitcnt vmcnt(7)
	v_lshlrev_b32_e32 v52, 16, v218
	v_and_b32_e32 v53, 0xffff0000, v218
	v_lshlrev_b32_e32 v54, 16, v219
	v_and_b32_e32 v55, 0xffff0000, v219
	v_fmac_f32_e32 v48, v44, v44
	v_fmac_f32_e32 v49, v46, v46
	v_cvt_pk_bf16_f32 v232, v44, v45
	v_cvt_pk_bf16_f32 v233, v46, v47
	v_lshl_add_u64 v[46:47], s[34:35], 0, v[92:93]
	v_lshl_add_u64 v[46:47], v[140:141], 1, v[46:47]
	v_pk_add_f32 v[42:43], v[42:43], v[54:55]
	v_pk_add_f32 v[40:41], v[40:41], v[52:53]
	s_waitcnt vmcnt(6)
	v_permlane16_swap_b32 v220, v222
	v_permlane16_swap_b32 v221, v223
	v_lshlrev_b32_e32 v56, 16, v220
	v_and_b32_e32 v57, 0xffff0000, v220
	v_lshlrev_b32_e32 v58, 16, v221
	v_and_b32_e32 v59, 0xffff0000, v221
	v_mul_f32_e32 v44, v41, v41
	v_mul_f32_e32 v45, v43, v43
	v_fmac_f32_e32 v44, v40, v40
	v_fmac_f32_e32 v45, v42, v42
	v_pk_add_f32 v[38:39], v[38:39], v[58:59]
	v_pk_add_f32 v[36:37], v[36:37], v[56:57]
	v_add_f32_e32 v44, v44, v45
	v_cvt_pk_bf16_f32 v234, v40, v41
	v_mul_f32_e32 v41, v37, v37
	v_mul_f32_e32 v45, v39, v39
	v_add_f32_e32 v48, v48, v49
	v_fmac_f32_e32 v41, v36, v36
	v_fmac_f32_e32 v45, v38, v38
	s_waitcnt vmcnt(6)
	v_lshlrev_b32_e32 v60, 16, v222
	v_and_b32_e32 v61, 0xffff0000, v222
	v_lshlrev_b32_e32 v62, 16, v223
	v_and_b32_e32 v63, 0xffff0000, v223
	v_add_f32_e32 v44, v48, v44
	v_add_f32_e32 v41, v41, v45
	v_add_f32_e32 v41, v44, v41
	v_pk_add_f32 v[34:35], v[34:35], v[62:63]
	v_pk_add_f32 v[44:45], v[32:33], v[60:61]
	v_mul_f32_e32 v33, v35, v35
	v_mul_f32_e32 v32, v45, v45
	v_fmac_f32_e32 v32, v44, v44
	v_fmac_f32_e32 v33, v34, v34
	v_add_f32_e32 v32, v32, v33
	v_add_f32_e32 v32, v41, v32
	v_mov_b32_e32 v33, v32
	v_mov_b32_e32 v254, v32
	s_nop 1
	v_permlane16_swap_b32 v33, v254
	v_cvt_pk_bf16_f32 v235, v42, v43
	s_nop 1
	v_permlane16_swap_b32 v232, v234
	v_permlane16_swap_b32 v233, v235
	v_lshl_add_u64 v[240:241], v[46:47], 0, v[242:243]
	global_store_dwordx4 v[240:241], v[232:235], off
	v_cvt_pk_bf16_f32 v236, v36, v37
	v_cvt_pk_bf16_f32 v237, v38, v39
	s_waitcnt lgkmcnt(0)
	v_add_f32_e32 v32, v254, v33
	v_mov_b32_e32 v33, v32
	v_mov_b32_e32 v254, v32
	s_nop 1
	v_permlane32_swap_b32 v33, v254
	v_cvt_pk_bf16_f32 v238, v44, v45
	v_cvt_pk_bf16_f32 v239, v34, v35
	s_nop 1
	v_permlane16_swap_b32 v236, v238
	v_permlane16_swap_b32 v237, v239
	v_lshl_add_u64 v[240:241], v[46:47], 0, v[242:243]
	global_store_dwordx4 v[240:241], v[236:239], off offset:256
	s_and_saveexec_b64 s[40:41], s[8:9]
	s_cbranch_execz .LBB0_765
	v_lshl_add_u64 v[34:35], v[80:81], 2, s[12:13]
	s_waitcnt lgkmcnt(0)
	v_add_f32_e32 v32, v254, v33
	global_atomic_add_f32 v[34:35], v32, off
.LBB0_765:
	s_or_b64 exec, exec, s[40:41]
	s_waitcnt vmcnt(7)
	v_permlane16_swap_b32 v224, v226
	v_permlane16_swap_b32 v225, v227
	v_lshlrev_b32_e32 v32, 16, v224
	s_waitcnt lgkmcnt(0)
	v_and_b32_e32 v33, 0xffff0000, v224
	v_lshlrev_b32_e32 v34, 16, v225
	v_and_b32_e32 v35, 0xffff0000, v225
	v_pk_add_f32 v[30:31], v[30:31], v[34:35]
	v_pk_add_f32 v[28:29], v[28:29], v[32:33]
	v_mul_f32_e32 v33, v31, v31
	v_mul_f32_e32 v32, v29, v29
	s_waitcnt vmcnt(7)
	v_lshlrev_b32_e32 v36, 16, v226
	v_and_b32_e32 v37, 0xffff0000, v226
	v_lshlrev_b32_e32 v38, 16, v227
	v_and_b32_e32 v39, 0xffff0000, v227
	v_fmac_f32_e32 v32, v28, v28
	v_fmac_f32_e32 v33, v30, v30
	v_cvt_pk_bf16_f32 v232, v28, v29
	v_cvt_pk_bf16_f32 v233, v30, v31
	v_lshl_add_u64 v[30:31], s[34:35], 0, v[78:79]
	v_lshl_add_u64 v[30:31], v[140:141], 1, v[30:31]
	v_pk_add_f32 v[26:27], v[26:27], v[38:39]
	v_pk_add_f32 v[24:25], v[24:25], v[36:37]
	s_waitcnt vmcnt(6)
	v_permlane16_swap_b32 v228, v230
	v_permlane16_swap_b32 v229, v231
	v_lshlrev_b32_e32 v40, 16, v228
	v_and_b32_e32 v41, 0xffff0000, v228
	v_lshlrev_b32_e32 v42, 16, v229
	v_and_b32_e32 v43, 0xffff0000, v229
	v_mul_f32_e32 v28, v25, v25
	v_mul_f32_e32 v29, v27, v27
	v_fmac_f32_e32 v28, v24, v24
	v_fmac_f32_e32 v29, v26, v26
	v_pk_add_f32 v[22:23], v[22:23], v[42:43]
	v_pk_add_f32 v[20:21], v[20:21], v[40:41]
	v_add_f32_e32 v28, v28, v29
	v_cvt_pk_bf16_f32 v234, v24, v25
	v_mul_f32_e32 v25, v21, v21
	v_mul_f32_e32 v29, v23, v23
	v_add_f32_e32 v32, v32, v33
	v_fmac_f32_e32 v25, v20, v20
	v_fmac_f32_e32 v29, v22, v22
	s_waitcnt vmcnt(6)
	v_lshlrev_b32_e32 v44, 16, v230
	v_and_b32_e32 v45, 0xffff0000, v230
	v_lshlrev_b32_e32 v46, 16, v231
	v_and_b32_e32 v47, 0xffff0000, v231
	v_add_f32_e32 v28, v32, v28
	v_add_f32_e32 v25, v25, v29
	v_add_f32_e32 v25, v28, v25
	v_pk_add_f32 v[18:19], v[18:19], v[46:47]
	v_pk_add_f32 v[28:29], v[16:17], v[44:45]
	v_mul_f32_e32 v17, v19, v19
	v_mul_f32_e32 v16, v29, v29
	v_fmac_f32_e32 v16, v28, v28
	v_fmac_f32_e32 v17, v18, v18
	v_add_f32_e32 v16, v16, v17
	v_add_f32_e32 v16, v25, v16
	v_mov_b32_e32 v17, v16
	v_mov_b32_e32 v254, v16
	s_nop 1
	v_permlane16_swap_b32 v17, v254
	v_cvt_pk_bf16_f32 v235, v26, v27
	s_nop 1
	v_permlane16_swap_b32 v232, v234
	v_permlane16_swap_b32 v233, v235
	v_lshl_add_u64 v[240:241], v[30:31], 0, v[242:243]
	global_store_dwordx4 v[240:241], v[232:235], off
	v_cvt_pk_bf16_f32 v236, v20, v21
	v_cvt_pk_bf16_f32 v237, v22, v23
	s_waitcnt lgkmcnt(0)
	v_add_f32_e32 v16, v254, v17
	v_mov_b32_e32 v17, v16
	v_mov_b32_e32 v254, v16
	s_nop 1
	v_permlane32_swap_b32 v17, v254
	v_cvt_pk_bf16_f32 v238, v28, v29
	v_cvt_pk_bf16_f32 v239, v18, v19
	s_nop 1
	v_permlane16_swap_b32 v236, v238
	v_permlane16_swap_b32 v237, v239
	v_lshl_add_u64 v[240:241], v[30:31], 0, v[242:243]
	global_store_dwordx4 v[240:241], v[236:239], off offset:256
	s_and_saveexec_b64 s[40:41], s[8:9]
	s_cbranch_execz .LBB0_767
	v_lshl_add_u64 v[18:19], v[68:69], 2, s[12:13]
	s_waitcnt lgkmcnt(0)
	v_add_f32_e32 v16, v254, v17
	global_atomic_add_f32 v[18:19], v16, off
.LBB0_767:
	s_or_b64 exec, exec, s[40:41]
	s_waitcnt vmcnt(7)
	v_permlane16_swap_b32 v244, v246
	v_permlane16_swap_b32 v245, v247
	v_lshlrev_b32_e32 v16, 16, v244
	s_waitcnt lgkmcnt(0)
	v_and_b32_e32 v17, 0xffff0000, v244
	v_lshlrev_b32_e32 v18, 16, v245
	v_and_b32_e32 v19, 0xffff0000, v245
	v_pk_add_f32 v[14:15], v[14:15], v[18:19]
	v_pk_add_f32 v[12:13], v[12:13], v[16:17]
	v_mul_f32_e32 v17, v15, v15
	v_mul_f32_e32 v16, v13, v13
	s_waitcnt vmcnt(7)
	v_lshlrev_b32_e32 v20, 16, v246
	v_and_b32_e32 v21, 0xffff0000, v246
	v_lshlrev_b32_e32 v22, 16, v247
	v_and_b32_e32 v23, 0xffff0000, v247
	v_fmac_f32_e32 v16, v12, v12
	v_fmac_f32_e32 v17, v14, v14
	v_cvt_pk_bf16_f32 v232, v12, v13
	v_cvt_pk_bf16_f32 v233, v14, v15
	v_lshl_add_u64 v[14:15], s[34:35], 0, v[66:67]
	v_lshl_add_u64 v[14:15], v[140:141], 1, v[14:15]
	v_pk_add_f32 v[10:11], v[10:11], v[22:23]
	v_pk_add_f32 v[8:9], v[8:9], v[20:21]
	s_waitcnt vmcnt(6)
	v_permlane16_swap_b32 v248, v250
	v_permlane16_swap_b32 v249, v251
	v_lshlrev_b32_e32 v24, 16, v248
	v_and_b32_e32 v25, 0xffff0000, v248
	v_lshlrev_b32_e32 v26, 16, v249
	v_and_b32_e32 v27, 0xffff0000, v249
	v_mul_f32_e32 v12, v9, v9
	v_mul_f32_e32 v13, v11, v11
	v_fmac_f32_e32 v12, v8, v8
	v_fmac_f32_e32 v13, v10, v10
	v_pk_add_f32 v[6:7], v[6:7], v[26:27]
	v_pk_add_f32 v[4:5], v[4:5], v[24:25]
	v_add_f32_e32 v12, v12, v13
	v_cvt_pk_bf16_f32 v234, v8, v9
	v_mul_f32_e32 v9, v5, v5
	v_mul_f32_e32 v13, v7, v7
	v_add_f32_e32 v16, v16, v17
	v_fmac_f32_e32 v9, v4, v4
	v_fmac_f32_e32 v13, v6, v6
	s_waitcnt vmcnt(6)
	v_lshlrev_b32_e32 v28, 16, v250
	v_and_b32_e32 v29, 0xffff0000, v250
	v_lshlrev_b32_e32 v30, 16, v251
	v_and_b32_e32 v31, 0xffff0000, v251
	v_add_f32_e32 v12, v16, v12
	v_add_f32_e32 v9, v9, v13
	v_add_f32_e32 v9, v12, v9
	v_pk_add_f32 v[2:3], v[2:3], v[30:31]
	v_pk_add_f32 v[12:13], v[0:1], v[28:29]
	v_mul_f32_e32 v1, v3, v3
	v_mul_f32_e32 v0, v13, v13
	v_fmac_f32_e32 v0, v12, v12
	v_fmac_f32_e32 v1, v2, v2
	v_add_f32_e32 v0, v0, v1
	v_add_f32_e32 v0, v9, v0
	v_mov_b32_e32 v1, v0
	v_mov_b32_e32 v254, v0
	s_nop 1
	v_permlane16_swap_b32 v1, v254
	v_cvt_pk_bf16_f32 v235, v10, v11
	s_nop 1
	v_permlane16_swap_b32 v232, v234
	v_permlane16_swap_b32 v233, v235
	v_lshl_add_u64 v[240:241], v[14:15], 0, v[242:243]
	global_store_dwordx4 v[240:241], v[232:235], off
	v_cvt_pk_bf16_f32 v236, v4, v5
	v_cvt_pk_bf16_f32 v237, v6, v7
	s_waitcnt lgkmcnt(0)
	v_add_f32_e32 v0, v254, v1
	v_mov_b32_e32 v1, v0
	v_mov_b32_e32 v254, v0
	s_nop 1
	v_permlane32_swap_b32 v1, v254
	v_cvt_pk_bf16_f32 v238, v12, v13
	v_cvt_pk_bf16_f32 v239, v2, v3
	s_nop 1
	v_permlane16_swap_b32 v236, v238
	v_permlane16_swap_b32 v237, v239
	v_lshl_add_u64 v[240:241], v[14:15], 0, v[242:243]
	global_store_dwordx4 v[240:241], v[236:239], off offset:256
	s_and_saveexec_b64 s[40:41], s[8:9]
	s_cbranch_execz .LBB0_769
	v_lshl_add_u64 v[2:3], v[64:65], 2, s[12:13]
	s_waitcnt lgkmcnt(0)
	v_add_f32_e32 v0, v254, v1
	global_atomic_add_f32 v[2:3], v0, off
